# plus attention QK as two back-to-back accumulate chains with K fragments prefetched, unscaled fp8 MFMA form, and no-op setprio pairs removed from GEMM loops
# baseline (speedup 1.0000x reference)
_Z6mk_fwd4Args:
	v_mov_b32_e32 v248, 0
	s_nop 0
	v_mov_b32_e32 v1, v0
	s_load_dwordx2 s[90:91], s[0:1], 0xe0
	s_load_dword s88, s[0:1], 0xf0
	s_load_dwordx8 s[4:11], s[0:1], 0xc0
	s_mov_b32 s92, s2
	s_add_u32 s2, s0, 0xf0
	s_addc_u32 s3, s1, 0
	v_readfirstlane_b32 s14, v1
	s_waitcnt lgkmcnt(0)
	v_writelane_b32 v245, s4, 0
	s_mov_b32 s16, s92
	s_nop 0
	v_writelane_b32 v245, s5, 1
	v_writelane_b32 v245, s6, 2
	v_writelane_b32 v245, s7, 3
	v_writelane_b32 v245, s8, 4
	v_writelane_b32 v245, s9, 5
	v_writelane_b32 v245, s10, 6
	v_writelane_b32 v245, s11, 7
	v_writelane_b32 v245, s2, 8
	s_nop 1
	v_writelane_b32 v245, s3, 9
	s_and_b32 s2, s88, 7
	s_cmp_lg_u32 s2, 0
	s_cbranch_scc1 .LBB0_2
	s_ashr_i32 s3, s92, 31
	s_lshr_b32 s3, s3, 29
	s_add_i32 s3, s92, s3
	s_and_b32 s4, s3, -8
	s_ashr_i32 s2, s88, 3
	s_sub_i32 s4, s92, s4
	s_mul_i32 s2, s2, s4
	s_ashr_i32 s3, s3, 3
	s_add_i32 s16, s2, s3

.LBB0_216:
	ds_read_b128 v[152:155], v160
	ds_read_b128 v[164:167], v160 offset:1024
	ds_read_b128 v[168:171], v160 offset:2048
	ds_read_b128 v[172:175], v160 offset:3072
	ds_read_b128 v[176:179], v161
	ds_read_b128 v[180:183], v161 offset:1024
	ds_read_b128 v[184:187], v161 offset:2048
	ds_read_b128 v[188:191], v161 offset:3072
	s_add_u32 s20, s0, 0xfff00080
	s_addc_u32 s21, s1, -1
	s_cmp_eq_u32 s30, 60
	s_cselect_b32 s23, s13, s21
	s_cselect_b32 s22, s24, s20
	s_cselect_b32 s21, s15, s29
	s_cselect_b32 s20, s25, s27
	v_lshl_add_u64 v[156:157], s[0:1], 0, v[140:141]
	s_add_i32 m0, s39, 0xc000
	ds_read_b128 v[192:195], v162
	ds_read_b128 v[196:199], v162 offset:1024
	ds_read_b128 v[200:203], v162 offset:2048
	ds_read_b128 v[204:207], v162 offset:3072
	ds_read_b128 v[208:211], v162 offset:4096
	ds_read_b128 v[212:215], v162 offset:5120
	ds_read_b128 v[216:219], v162 offset:6144
	ds_read_b128 v[220:223], v162 offset:7168
	global_load_lds_dwordx4 v[156:157], off
	v_lshl_add_u64 v[156:157], s[0:1], 0, v[142:143]
	s_add_i32 m0, s39, 0xe000
	s_nop 0
	global_load_lds_dwordx4 v[156:157], off
	s_waitcnt vmcnt(8)
	s_waitcnt lgkmcnt(0)
	s_barrier
	s_setprio 1
	s_waitcnt lgkmcnt(0)
	v_mfma_f32_16x16x32_bf16 v[126:129], v[152:155], v[192:195], v[126:129]
	v_mfma_f32_16x16x32_bf16 v[122:125], v[168:171], v[192:195], v[122:125]
	v_mfma_f32_16x16x32_bf16 v[114:117], v[152:155], v[200:203], v[114:117]
	v_mfma_f32_16x16x32_bf16 v[106:109], v[168:171], v[200:203], v[106:109]
	v_mfma_f32_16x16x32_bf16 v[98:101], v[152:155], v[208:211], v[98:101]
	v_mfma_f32_16x16x32_bf16 v[90:93], v[168:171], v[208:211], v[90:93]
	v_mfma_f32_16x16x32_bf16 v[82:85], v[152:155], v[216:219], v[82:85]
	v_mfma_f32_16x16x32_bf16 v[74:77], v[168:171], v[216:219], v[74:77]
	v_mfma_f32_16x16x32_bf16 v[126:129], v[164:167], v[196:199], v[126:129]
	v_mfma_f32_16x16x32_bf16 v[122:125], v[172:175], v[196:199], v[122:125]
	v_mfma_f32_16x16x32_bf16 v[114:117], v[164:167], v[204:207], v[114:117]
	v_mfma_f32_16x16x32_bf16 v[106:109], v[172:175], v[204:207], v[106:109]
	v_mfma_f32_16x16x32_bf16 v[98:101], v[164:167], v[212:215], v[98:101]
	v_mfma_f32_16x16x32_bf16 v[90:93], v[172:175], v[212:215], v[90:93]
	v_mfma_f32_16x16x32_bf16 v[82:85], v[164:167], v[220:223], v[82:85]
	v_mfma_f32_16x16x32_bf16 v[74:77], v[172:175], v[220:223], v[74:77]
	s_setprio 0
	s_setprio 1
	v_mfma_f32_16x16x32_bf16 v[118:121], v[176:179], v[192:195], v[118:121]
	v_mfma_f32_16x16x32_bf16 v[110:113], v[184:187], v[192:195], v[110:113]
	v_mfma_f32_16x16x32_bf16 v[102:105], v[176:179], v[200:203], v[102:105]
	v_mfma_f32_16x16x32_bf16 v[94:97], v[184:187], v[200:203], v[94:97]
	v_mfma_f32_16x16x32_bf16 v[86:89], v[176:179], v[208:211], v[86:89]
	v_mfma_f32_16x16x32_bf16 v[78:81], v[184:187], v[208:211], v[78:81]
	v_mfma_f32_16x16x32_bf16 v[70:73], v[176:179], v[216:219], v[70:73]
	v_mfma_f32_16x16x32_bf16 v[66:69], v[184:187], v[216:219], v[66:69]
	v_mfma_f32_16x16x32_bf16 v[118:121], v[180:183], v[196:199], v[118:121]
	v_mfma_f32_16x16x32_bf16 v[110:113], v[188:191], v[196:199], v[110:113]
	v_mfma_f32_16x16x32_bf16 v[102:105], v[180:183], v[204:207], v[102:105]
	v_mfma_f32_16x16x32_bf16 v[94:97], v[188:191], v[204:207], v[94:97]
	v_mfma_f32_16x16x32_bf16 v[86:89], v[180:183], v[212:215], v[86:89]
	v_mfma_f32_16x16x32_bf16 v[78:81], v[188:191], v[212:215], v[78:81]
	v_mfma_f32_16x16x32_bf16 v[70:73], v[180:183], v[220:223], v[70:73]
	v_mfma_f32_16x16x32_bf16 v[66:69], v[188:191], v[220:223], v[66:69]
	s_setprio 0
	s_barrier
	s_add_i32 s31, s49, s38
	v_lshl_add_u64 v[156:157], s[20:21], 0, v[132:133]
	s_mov_b32 m0, s31
	ds_read_b128 v[192:195], v162 offset:16384
	ds_read_b128 v[196:199], v162 offset:17408
	ds_read_b128 v[200:203], v162 offset:18432
	ds_read_b128 v[204:207], v162 offset:19456
	ds_read_b128 v[208:211], v162 offset:20480
	ds_read_b128 v[212:215], v162 offset:21504
	ds_read_b128 v[216:219], v162 offset:22528
	ds_read_b128 v[220:223], v162 offset:23552
	global_load_lds_dwordx4 v[156:157], off
	s_add_i32 m0, s31, 0x2000
	s_add_u32 s34, s20, 0x100000
	v_lshl_add_u64 v[224:225], s[20:21], 0, v[136:137]
	s_addc_u32 s35, s21, 0
	s_add_i32 s31, s50, s38
	global_load_lds_dwordx4 v[224:225], off
	v_lshl_add_u64 v[226:227], s[34:35], 0, v[132:133]
	s_mov_b32 m0, s31
	v_lshl_add_u64 v[228:229], s[22:23], 0, v[134:135]
	global_load_lds_dwordx4 v[226:227], off
	v_lshl_add_u64 v[226:227], s[34:35], 0, v[136:137]
	s_add_i32 m0, s31, 0x2000
	s_nop 0
	global_load_lds_dwordx4 v[226:227], off
	v_lshl_add_u64 v[226:227], s[22:23], 0, v[130:131]
	s_mov_b32 m0, s39
	s_nop 0
	global_load_lds_dwordx4 v[226:227], off
	s_mov_b32 m0, s40
	s_nop 0
	global_load_lds_dwordx4 v[228:229], off
	s_waitcnt vmcnt(8)
	s_waitcnt lgkmcnt(0)
	s_barrier
	s_setprio 1
	s_waitcnt lgkmcnt(0)
	v_mfma_f32_16x16x32_bf16 v[62:65], v[152:155], v[192:195], v[62:65]
	v_mfma_f32_16x16x32_bf16 v[58:61], v[168:171], v[192:195], v[58:61]
	v_mfma_f32_16x16x32_bf16 v[46:49], v[152:155], v[200:203], v[46:49]
	v_mfma_f32_16x16x32_bf16 v[42:45], v[168:171], v[200:203], v[42:45]
	v_mfma_f32_16x16x32_bf16 v[30:33], v[152:155], v[208:211], v[30:33]
	v_mfma_f32_16x16x32_bf16 v[26:29], v[168:171], v[208:211], v[26:29]
	v_mfma_f32_16x16x32_bf16 v[14:17], v[152:155], v[216:219], v[14:17]
	v_mfma_f32_16x16x32_bf16 v[10:13], v[168:171], v[216:219], v[10:13]
	v_mfma_f32_16x16x32_bf16 v[62:65], v[164:167], v[196:199], v[62:65]
	v_mfma_f32_16x16x32_bf16 v[58:61], v[172:175], v[196:199], v[58:61]
	v_mfma_f32_16x16x32_bf16 v[46:49], v[164:167], v[204:207], v[46:49]
	v_mfma_f32_16x16x32_bf16 v[42:45], v[172:175], v[204:207], v[42:45]
	v_mfma_f32_16x16x32_bf16 v[30:33], v[164:167], v[212:215], v[30:33]
	v_mfma_f32_16x16x32_bf16 v[26:29], v[172:175], v[212:215], v[26:29]
	v_mfma_f32_16x16x32_bf16 v[14:17], v[164:167], v[220:223], v[14:17]
	v_mfma_f32_16x16x32_bf16 v[10:13], v[172:175], v[220:223], v[10:13]
	s_setprio 0
	s_setprio 1
	v_mfma_f32_16x16x32_bf16 v[54:57], v[176:179], v[192:195], v[54:57]
	v_mfma_f32_16x16x32_bf16 v[50:53], v[184:187], v[192:195], v[50:53]
	v_mfma_f32_16x16x32_bf16 v[38:41], v[176:179], v[200:203], v[38:41]
	v_mfma_f32_16x16x32_bf16 v[34:37], v[184:187], v[200:203], v[34:37]
	v_mfma_f32_16x16x32_bf16 v[22:25], v[176:179], v[208:211], v[22:25]
	v_mfma_f32_16x16x32_bf16 v[18:21], v[184:187], v[208:211], v[18:21]
	v_mfma_f32_16x16x32_bf16 v[6:9], v[176:179], v[216:219], v[6:9]
	v_mfma_f32_16x16x32_bf16 v[2:5], v[184:187], v[216:219], v[2:5]
	v_mfma_f32_16x16x32_bf16 v[54:57], v[180:183], v[196:199], v[54:57]
	v_mfma_f32_16x16x32_bf16 v[50:53], v[188:191], v[196:199], v[50:53]
	v_mfma_f32_16x16x32_bf16 v[38:41], v[180:183], v[204:207], v[38:41]
	v_mfma_f32_16x16x32_bf16 v[34:37], v[188:191], v[204:207], v[34:37]
	v_mfma_f32_16x16x32_bf16 v[22:25], v[180:183], v[212:215], v[22:25]
	v_mfma_f32_16x16x32_bf16 v[18:21], v[188:191], v[212:215], v[18:21]
	v_mfma_f32_16x16x32_bf16 v[6:9], v[180:183], v[220:223], v[6:9]
	v_mfma_f32_16x16x32_bf16 v[2:5], v[188:191], v[220:223], v[2:5]
	s_setprio 0
	s_barrier
	s_add_i32 s31, 0, 0x18000
	v_add_u32_e32 v138, s31, v158
	s_add_i32 s33, 0, 0x1c000
	ds_read_b128 v[152:155], v138
	ds_read_b128 v[164:167], v138 offset:1024
	ds_read_b128 v[168:171], v138 offset:2048
	ds_read_b128 v[172:175], v138 offset:3072
	v_add_u32_e32 v138, s33, v158
	ds_read_b128 v[176:179], v138
	ds_read_b128 v[180:183], v138 offset:1024
	ds_read_b128 v[184:187], v138 offset:2048
	ds_read_b128 v[188:191], v138 offset:3072
	s_add_u32 s22, s22, 0x100000
	s_addc_u32 s23, s23, 0
	s_mov_b32 m0, s41
	v_lshl_add_u64 v[230:231], s[22:23], 0, v[130:131]
	ds_read_b128 v[192:195], v162 offset:32768
	ds_read_b128 v[196:199], v162 offset:33792
	ds_read_b128 v[200:203], v162 offset:34816
	ds_read_b128 v[204:207], v162 offset:35840
	ds_read_b128 v[208:211], v162 offset:36864
	ds_read_b128 v[212:215], v162 offset:37888
	ds_read_b128 v[216:219], v162 offset:38912
	ds_read_b128 v[220:223], v162 offset:39936
	global_load_lds_dwordx4 v[230:231], off
	v_lshl_add_u64 v[230:231], s[22:23], 0, v[134:135]
	s_mov_b32 m0, s42
	s_nop 0
	global_load_lds_dwordx4 v[230:231], off
	s_waitcnt vmcnt(8)
	s_waitcnt lgkmcnt(0)
	s_barrier
	s_setprio 1
	s_waitcnt lgkmcnt(0)
	v_mfma_f32_16x16x32_bf16 v[126:129], v[152:155], v[192:195], v[126:129]
	v_mfma_f32_16x16x32_bf16 v[122:125], v[168:171], v[192:195], v[122:125]
	v_mfma_f32_16x16x32_bf16 v[114:117], v[152:155], v[200:203], v[114:117]
	v_mfma_f32_16x16x32_bf16 v[106:109], v[168:171], v[200:203], v[106:109]
	v_mfma_f32_16x16x32_bf16 v[98:101], v[152:155], v[208:211], v[98:101]
	v_mfma_f32_16x16x32_bf16 v[90:93], v[168:171], v[208:211], v[90:93]
	v_mfma_f32_16x16x32_bf16 v[82:85], v[152:155], v[216:219], v[82:85]
	v_mfma_f32_16x16x32_bf16 v[74:77], v[168:171], v[216:219], v[74:77]
	v_mfma_f32_16x16x32_bf16 v[126:129], v[164:167], v[196:199], v[126:129]
	v_mfma_f32_16x16x32_bf16 v[122:125], v[172:175], v[196:199], v[122:125]
	v_mfma_f32_16x16x32_bf16 v[114:117], v[164:167], v[204:207], v[114:117]
	v_mfma_f32_16x16x32_bf16 v[106:109], v[172:175], v[204:207], v[106:109]
	v_mfma_f32_16x16x32_bf16 v[98:101], v[164:167], v[212:215], v[98:101]
	v_mfma_f32_16x16x32_bf16 v[90:93], v[172:175], v[212:215], v[90:93]
	v_mfma_f32_16x16x32_bf16 v[82:85], v[164:167], v[220:223], v[82:85]
	v_mfma_f32_16x16x32_bf16 v[74:77], v[172:175], v[220:223], v[74:77]
	s_setprio 0
	s_setprio 1
	v_mfma_f32_16x16x32_bf16 v[118:121], v[176:179], v[192:195], v[118:121]
	v_mfma_f32_16x16x32_bf16 v[110:113], v[184:187], v[192:195], v[110:113]
	v_mfma_f32_16x16x32_bf16 v[102:105], v[176:179], v[200:203], v[102:105]
	v_mfma_f32_16x16x32_bf16 v[94:97], v[184:187], v[200:203], v[94:97]
	v_mfma_f32_16x16x32_bf16 v[86:89], v[176:179], v[208:211], v[86:89]
	v_mfma_f32_16x16x32_bf16 v[78:81], v[184:187], v[208:211], v[78:81]
	v_mfma_f32_16x16x32_bf16 v[70:73], v[176:179], v[216:219], v[70:73]
	v_mfma_f32_16x16x32_bf16 v[66:69], v[184:187], v[216:219], v[66:69]
	v_mfma_f32_16x16x32_bf16 v[118:121], v[180:183], v[196:199], v[118:121]
	v_mfma_f32_16x16x32_bf16 v[110:113], v[188:191], v[196:199], v[110:113]
	v_mfma_f32_16x16x32_bf16 v[102:105], v[180:183], v[204:207], v[102:105]
	v_mfma_f32_16x16x32_bf16 v[94:97], v[188:191], v[204:207], v[94:97]
	v_mfma_f32_16x16x32_bf16 v[86:89], v[180:183], v[212:215], v[86:89]
	v_mfma_f32_16x16x32_bf16 v[78:81], v[188:191], v[212:215], v[78:81]
	v_mfma_f32_16x16x32_bf16 v[70:73], v[180:183], v[220:223], v[70:73]
	v_mfma_f32_16x16x32_bf16 v[66:69], v[188:191], v[220:223], v[66:69]
	s_setprio 0
	s_barrier
	s_add_i32 s22, s31, s38
	v_lshl_add_u64 v[156:157], v[156:157], 0, s[8:9]
	s_mov_b32 m0, s22
	ds_read_b128 v[192:195], v162 offset:49152
	ds_read_b128 v[196:199], v162 offset:50176
	ds_read_b128 v[200:203], v162 offset:51200
	ds_read_b128 v[204:207], v162 offset:52224
	ds_read_b128 v[208:211], v162 offset:53248
	ds_read_b128 v[212:215], v162 offset:54272
	ds_read_b128 v[216:219], v162 offset:55296
	ds_read_b128 v[220:223], v162 offset:56320
	global_load_lds_dwordx4 v[156:157], off
	s_add_i32 m0, s22, 0x2000
	s_add_u32 s20, s20, 0x100080
	v_lshl_add_u64 v[156:157], v[224:225], 0, s[8:9]
	s_addc_u32 s21, s21, 0
	s_add_i32 s22, s33, s38
	global_load_lds_dwordx4 v[156:157], off
	v_lshl_add_u64 v[156:157], s[20:21], 0, v[132:133]
	s_mov_b32 m0, s22
	s_nop 0
	global_load_lds_dwordx4 v[156:157], off
	v_lshl_add_u64 v[156:157], s[20:21], 0, v[136:137]
	s_add_i32 m0, s22, 0x2000
	s_nop 0
	global_load_lds_dwordx4 v[156:157], off
	v_lshl_add_u64 v[156:157], v[226:227], 0, s[8:9]
	s_mov_b32 m0, s45
	s_nop 0
	global_load_lds_dwordx4 v[156:157], off
	v_lshl_add_u64 v[156:157], v[228:229], 0, s[8:9]
	s_mov_b32 m0, s46
	s_nop 0
	global_load_lds_dwordx4 v[156:157], off
	s_waitcnt vmcnt(8)
	s_waitcnt lgkmcnt(0)
	s_barrier
	s_setprio 1
	s_waitcnt lgkmcnt(0)
	v_mfma_f32_16x16x32_bf16 v[62:65], v[152:155], v[192:195], v[62:65]
	v_mfma_f32_16x16x32_bf16 v[58:61], v[168:171], v[192:195], v[58:61]
	v_mfma_f32_16x16x32_bf16 v[46:49], v[152:155], v[200:203], v[46:49]
	v_mfma_f32_16x16x32_bf16 v[42:45], v[168:171], v[200:203], v[42:45]
	v_mfma_f32_16x16x32_bf16 v[30:33], v[152:155], v[208:211], v[30:33]
	v_mfma_f32_16x16x32_bf16 v[26:29], v[168:171], v[208:211], v[26:29]
	v_mfma_f32_16x16x32_bf16 v[14:17], v[152:155], v[216:219], v[14:17]
	v_mfma_f32_16x16x32_bf16 v[10:13], v[168:171], v[216:219], v[10:13]
	v_mfma_f32_16x16x32_bf16 v[62:65], v[164:167], v[196:199], v[62:65]
	v_mfma_f32_16x16x32_bf16 v[58:61], v[172:175], v[196:199], v[58:61]
	v_mfma_f32_16x16x32_bf16 v[46:49], v[164:167], v[204:207], v[46:49]
	v_mfma_f32_16x16x32_bf16 v[42:45], v[172:175], v[204:207], v[42:45]
	v_mfma_f32_16x16x32_bf16 v[30:33], v[164:167], v[212:215], v[30:33]
	v_mfma_f32_16x16x32_bf16 v[26:29], v[172:175], v[212:215], v[26:29]
	v_mfma_f32_16x16x32_bf16 v[14:17], v[164:167], v[220:223], v[14:17]
	v_mfma_f32_16x16x32_bf16 v[10:13], v[172:175], v[220:223], v[10:13]
	s_setprio 0
	s_setprio 1
	v_mfma_f32_16x16x32_bf16 v[54:57], v[176:179], v[192:195], v[54:57]
	v_mfma_f32_16x16x32_bf16 v[50:53], v[184:187], v[192:195], v[50:53]
	v_mfma_f32_16x16x32_bf16 v[38:41], v[176:179], v[200:203], v[38:41]
	v_mfma_f32_16x16x32_bf16 v[34:37], v[184:187], v[200:203], v[34:37]
	v_mfma_f32_16x16x32_bf16 v[22:25], v[176:179], v[208:211], v[22:25]
	v_mfma_f32_16x16x32_bf16 v[18:21], v[184:187], v[208:211], v[18:21]
	v_mfma_f32_16x16x32_bf16 v[6:9], v[176:179], v[216:219], v[6:9]
	v_mfma_f32_16x16x32_bf16 v[2:5], v[184:187], v[216:219], v[2:5]
	v_mfma_f32_16x16x32_bf16 v[54:57], v[180:183], v[196:199], v[54:57]
	v_mfma_f32_16x16x32_bf16 v[50:53], v[188:191], v[196:199], v[50:53]
	v_mfma_f32_16x16x32_bf16 v[38:41], v[180:183], v[204:207], v[38:41]
	v_mfma_f32_16x16x32_bf16 v[34:37], v[188:191], v[204:207], v[34:37]
	v_mfma_f32_16x16x32_bf16 v[22:25], v[180:183], v[212:215], v[22:25]
	v_mfma_f32_16x16x32_bf16 v[18:21], v[188:191], v[212:215], v[18:21]
	v_mfma_f32_16x16x32_bf16 v[6:9], v[180:183], v[220:223], v[6:9]
	v_mfma_f32_16x16x32_bf16 v[2:5], v[188:191], v[220:223], v[2:5]
	s_setprio 0
	s_barrier
	s_add_i32 s30, s30, 2
	s_add_u32 s0, s0, 0x100
	s_addc_u32 s1, s1, 0
	s_add_u32 s27, s27, 0x100
	s_addc_u32 s29, s29, 0
	s_cmp_gt_u32 s30, 61
	s_cbranch_scc0 .LBB0_216
	s_and_b64 vcc, exec, s[10:11]
	s_cbranch_vccz .LBB0_219
	s_barrier

.LBB0_271:
	ds_read_b128 v[26:29], v183
	ds_read_b128 v[30:33], v183 offset:16
	ds_read_b128 v[18:21], v183 offset:2048
	ds_read_b128 v[22:25], v183 offset:2064
	ds_read_b128 v[10:13], v184
	ds_read_b128 v[14:17], v184 offset:16
	ds_read_b128 v[2:5], v184 offset:2048
	ds_read_b128 v[6:9], v184 offset:2064
	s_add_u32 s0, s20, 0xfff80080
	s_addc_u32 s1, s21, -1
	s_cmp_eq_u32 s29, 28
	s_cselect_b32 s23, s13, s1
	s_cselect_b32 s22, s25, s0
	s_cselect_b32 s1, s11, s28
	s_cselect_b32 s0, s26, s27
	v_lshl_add_u64 v[212:213], s[20:21], 0, v[162:163]
	s_add_i32 m0, s19, 0xc000
	ds_read_b128 v[174:177], v185
	ds_read_b128 v[178:181], v185 offset:16
	ds_read_b128 v[188:191], v185 offset:2048
	ds_read_b128 v[192:195], v185 offset:2064
	ds_read_b128 v[196:199], v185 offset:4096
	ds_read_b128 v[200:203], v185 offset:4112
	ds_read_b128 v[204:207], v185 offset:6144
	ds_read_b128 v[208:211], v185 offset:6160
	global_load_lds_dwordx4 v[212:213], off
	v_lshl_add_u64 v[212:213], s[20:21], 0, v[172:173]
	s_add_i32 m0, s19, 0xe000
	s_nop 0
	global_load_lds_dwordx4 v[212:213], off
	s_waitcnt vmcnt(8)
	s_waitcnt lgkmcnt(0)
	s_barrier
	s_setprio 1
	s_waitcnt lgkmcnt(0)
	v_mfma_scale_f32_16x16x128_f8f6f4 v[158:161], v[26:33], v[174:181], v[158:161], v186, v186 op_sel_hi:[0,0,0]
	v_mfma_scale_f32_16x16x128_f8f6f4 v[154:157], v[18:25], v[174:181], v[154:157], v186, v186 op_sel_hi:[0,0,0]
	v_mfma_scale_f32_16x16x128_f8f6f4 v[146:149], v[26:33], v[188:195], v[146:149], v186, v186 op_sel_hi:[0,0,0]
	v_mfma_scale_f32_16x16x128_f8f6f4 v[138:141], v[18:25], v[188:195], v[138:141], v186, v186 op_sel_hi:[0,0,0]
	v_mfma_scale_f32_16x16x128_f8f6f4 v[130:133], v[26:33], v[196:203], v[130:133], v186, v186 op_sel_hi:[0,0,0]
	v_mfma_scale_f32_16x16x128_f8f6f4 v[122:125], v[18:25], v[196:203], v[122:125], v186, v186 op_sel_hi:[0,0,0]
	v_mfma_scale_f32_16x16x128_f8f6f4 v[114:117], v[26:33], v[204:211], v[114:117], v186, v186 op_sel_hi:[0,0,0]
	v_mfma_scale_f32_16x16x128_f8f6f4 v[106:109], v[18:25], v[204:211], v[106:109], v186, v186 op_sel_hi:[0,0,0]
	s_setprio 0
	s_setprio 1
	v_mfma_scale_f32_16x16x128_f8f6f4 v[150:153], v[10:17], v[174:181], v[150:153], v186, v186 op_sel_hi:[0,0,0]
	v_mfma_scale_f32_16x16x128_f8f6f4 v[142:145], v[2:9], v[174:181], v[142:145], v186, v186 op_sel_hi:[0,0,0]
	v_mfma_scale_f32_16x16x128_f8f6f4 v[134:137], v[10:17], v[188:195], v[134:137], v186, v186 op_sel_hi:[0,0,0]
	v_mfma_scale_f32_16x16x128_f8f6f4 v[126:129], v[2:9], v[188:195], v[126:129], v186, v186 op_sel_hi:[0,0,0]
	v_mfma_scale_f32_16x16x128_f8f6f4 v[118:121], v[10:17], v[196:203], v[118:121], v186, v186 op_sel_hi:[0,0,0]
	v_mfma_scale_f32_16x16x128_f8f6f4 v[110:113], v[2:9], v[196:203], v[110:113], v186, v186 op_sel_hi:[0,0,0]
	v_mfma_scale_f32_16x16x128_f8f6f4 v[102:105], v[10:17], v[204:211], v[102:105], v186, v186 op_sel_hi:[0,0,0]
	v_mfma_scale_f32_16x16x128_f8f6f4 v[98:101], v[2:9], v[204:211], v[98:101], v186, v186 op_sel_hi:[0,0,0]
	s_setprio 0
	s_barrier
	s_add_i32 s30, s48, s37
	v_lshl_add_u64 v[174:175], s[0:1], 0, v[168:169]
	s_mov_b32 m0, s30
	ds_read_b128 v[188:191], v185 offset:16384
	ds_read_b128 v[192:195], v185 offset:16400
	ds_read_b128 v[196:199], v185 offset:18432
	ds_read_b128 v[200:203], v185 offset:18448
	ds_read_b128 v[204:207], v185 offset:20480
	ds_read_b128 v[208:211], v185 offset:20496
	ds_read_b128 v[212:215], v185 offset:22528
	ds_read_b128 v[216:219], v185 offset:22544
	global_load_lds_dwordx4 v[174:175], off
	s_add_i32 m0, s30, 0x2000
	s_add_u32 s30, s0, 0x80000
	v_lshl_add_u64 v[176:177], s[0:1], 0, v[170:171]
	s_addc_u32 s31, s1, 0
	s_add_i32 s33, s49, s37
	global_load_lds_dwordx4 v[176:177], off
	v_lshl_add_u64 v[178:179], s[30:31], 0, v[168:169]
	s_mov_b32 m0, s33
	v_lshl_add_u64 v[180:181], s[22:23], 0, v[172:173]
	global_load_lds_dwordx4 v[178:179], off
	v_lshl_add_u64 v[178:179], s[30:31], 0, v[170:171]
	s_add_i32 m0, s33, 0x2000
	s_nop 0
	global_load_lds_dwordx4 v[178:179], off
	v_lshl_add_u64 v[178:179], s[22:23], 0, v[162:163]
	s_mov_b32 m0, s19
	s_nop 0
	global_load_lds_dwordx4 v[178:179], off
	s_mov_b32 m0, s38
	s_nop 0
	global_load_lds_dwordx4 v[180:181], off
	s_waitcnt vmcnt(8)
	s_waitcnt lgkmcnt(0)
	s_barrier
	s_setprio 1
	s_waitcnt lgkmcnt(0)
	v_mfma_scale_f32_16x16x128_f8f6f4 v[94:97], v[26:33], v[188:195], v[94:97], v186, v186 op_sel_hi:[0,0,0]
	v_mfma_scale_f32_16x16x128_f8f6f4 v[90:93], v[18:25], v[188:195], v[90:93], v186, v186 op_sel_hi:[0,0,0]
	v_mfma_scale_f32_16x16x128_f8f6f4 v[78:81], v[26:33], v[196:203], v[78:81], v186, v186 op_sel_hi:[0,0,0]
	v_mfma_scale_f32_16x16x128_f8f6f4 v[74:77], v[18:25], v[196:203], v[74:77], v186, v186 op_sel_hi:[0,0,0]
	v_mfma_scale_f32_16x16x128_f8f6f4 v[62:65], v[26:33], v[204:211], v[62:65], v186, v186 op_sel_hi:[0,0,0]
	v_mfma_scale_f32_16x16x128_f8f6f4 v[58:61], v[18:25], v[204:211], v[58:61], v186, v186 op_sel_hi:[0,0,0]
	v_mfma_scale_f32_16x16x128_f8f6f4 v[46:49], v[26:33], v[212:219], v[46:49], v186, v186 op_sel_hi:[0,0,0]
	v_mfma_scale_f32_16x16x128_f8f6f4 v[42:45], v[18:25], v[212:219], v[42:45], v186, v186 op_sel_hi:[0,0,0]
	s_setprio 0
	s_setprio 1
	v_mfma_scale_f32_16x16x128_f8f6f4 v[86:89], v[10:17], v[188:195], v[86:89], v186, v186 op_sel_hi:[0,0,0]
	v_mfma_scale_f32_16x16x128_f8f6f4 v[82:85], v[2:9], v[188:195], v[82:85], v186, v186 op_sel_hi:[0,0,0]
	v_mfma_scale_f32_16x16x128_f8f6f4 v[70:73], v[10:17], v[196:203], v[70:73], v186, v186 op_sel_hi:[0,0,0]
	v_mfma_scale_f32_16x16x128_f8f6f4 v[66:69], v[2:9], v[196:203], v[66:69], v186, v186 op_sel_hi:[0,0,0]
	v_mfma_scale_f32_16x16x128_f8f6f4 v[54:57], v[10:17], v[204:211], v[54:57], v186, v186 op_sel_hi:[0,0,0]
	v_mfma_scale_f32_16x16x128_f8f6f4 v[50:53], v[2:9], v[204:211], v[50:53], v186, v186 op_sel_hi:[0,0,0]
	v_mfma_scale_f32_16x16x128_f8f6f4 v[38:41], v[10:17], v[212:219], v[38:41], v186, v186 op_sel_hi:[0,0,0]
	v_mfma_scale_f32_16x16x128_f8f6f4 v[34:37], v[2:9], v[212:219], v[34:37], v186, v186 op_sel_hi:[0,0,0]
	s_setprio 0
	s_barrier
	s_add_i32 s30, 0, 0x18000
	s_add_i32 s31, 0, 0x1c000
	v_add_u32_e32 v14, s30, v182
	v_add_u32_e32 v30, s31, v182
	ds_read_b128 v[2:5], v14
	ds_read_b128 v[6:9], v14 offset:16
	ds_read_b128 v[10:13], v14 offset:2048
	ds_read_b128 v[14:17], v14 offset:2064
	ds_read_b128 v[18:21], v30
	ds_read_b128 v[22:25], v30 offset:16
	ds_read_b128 v[26:29], v30 offset:2048
	ds_read_b128 v[30:33], v30 offset:2064
	s_add_u32 s22, s22, 0x80000
	s_addc_u32 s23, s23, 0
	s_mov_b32 m0, s39
	v_lshl_add_u64 v[220:221], s[22:23], 0, v[162:163]
	ds_read_b128 v[188:191], v185 offset:32768
	ds_read_b128 v[192:195], v185 offset:32784
	ds_read_b128 v[196:199], v185 offset:34816
	ds_read_b128 v[200:203], v185 offset:34832
	ds_read_b128 v[204:207], v185 offset:36864
	ds_read_b128 v[208:211], v185 offset:36880
	ds_read_b128 v[212:215], v185 offset:38912
	ds_read_b128 v[216:219], v185 offset:38928
	global_load_lds_dwordx4 v[220:221], off
	v_lshl_add_u64 v[220:221], s[22:23], 0, v[172:173]
	s_mov_b32 m0, s40
	s_nop 0
	global_load_lds_dwordx4 v[220:221], off
	s_waitcnt vmcnt(8)
	s_waitcnt lgkmcnt(0)
	s_barrier
	s_setprio 1
	s_waitcnt lgkmcnt(0)
	v_mfma_scale_f32_16x16x128_f8f6f4 v[158:161], v[2:9], v[188:195], v[158:161], v186, v186 op_sel_hi:[0,0,0]
	v_mfma_scale_f32_16x16x128_f8f6f4 v[154:157], v[10:17], v[188:195], v[154:157], v186, v186 op_sel_hi:[0,0,0]
	v_mfma_scale_f32_16x16x128_f8f6f4 v[146:149], v[2:9], v[196:203], v[146:149], v186, v186 op_sel_hi:[0,0,0]
	v_mfma_scale_f32_16x16x128_f8f6f4 v[138:141], v[10:17], v[196:203], v[138:141], v186, v186 op_sel_hi:[0,0,0]
	v_mfma_scale_f32_16x16x128_f8f6f4 v[130:133], v[2:9], v[204:211], v[130:133], v186, v186 op_sel_hi:[0,0,0]
	v_mfma_scale_f32_16x16x128_f8f6f4 v[122:125], v[10:17], v[204:211], v[122:125], v186, v186 op_sel_hi:[0,0,0]
	v_mfma_scale_f32_16x16x128_f8f6f4 v[114:117], v[2:9], v[212:219], v[114:117], v186, v186 op_sel_hi:[0,0,0]
	v_mfma_scale_f32_16x16x128_f8f6f4 v[106:109], v[10:17], v[212:219], v[106:109], v186, v186 op_sel_hi:[0,0,0]
	s_setprio 0
	s_setprio 1
	v_mfma_scale_f32_16x16x128_f8f6f4 v[150:153], v[18:25], v[188:195], v[150:153], v186, v186 op_sel_hi:[0,0,0]
	v_mfma_scale_f32_16x16x128_f8f6f4 v[142:145], v[26:33], v[188:195], v[142:145], v186, v186 op_sel_hi:[0,0,0]
	v_mfma_scale_f32_16x16x128_f8f6f4 v[134:137], v[18:25], v[196:203], v[134:137], v186, v186 op_sel_hi:[0,0,0]
	v_mfma_scale_f32_16x16x128_f8f6f4 v[126:129], v[26:33], v[196:203], v[126:129], v186, v186 op_sel_hi:[0,0,0]
	v_mfma_scale_f32_16x16x128_f8f6f4 v[118:121], v[18:25], v[204:211], v[118:121], v186, v186 op_sel_hi:[0,0,0]
	v_mfma_scale_f32_16x16x128_f8f6f4 v[110:113], v[26:33], v[204:211], v[110:113], v186, v186 op_sel_hi:[0,0,0]
	v_mfma_scale_f32_16x16x128_f8f6f4 v[102:105], v[18:25], v[212:219], v[102:105], v186, v186 op_sel_hi:[0,0,0]
	v_mfma_scale_f32_16x16x128_f8f6f4 v[98:101], v[26:33], v[212:219], v[98:101], v186, v186 op_sel_hi:[0,0,0]
	s_setprio 0
	s_barrier
	s_add_i32 s22, s30, s37
	v_lshl_add_u64 v[174:175], v[174:175], 0, s[6:7]
	s_mov_b32 m0, s22
	ds_read_b128 v[188:191], v185 offset:49152
	ds_read_b128 v[192:195], v185 offset:49168
	ds_read_b128 v[196:199], v185 offset:51200
	ds_read_b128 v[200:203], v185 offset:51216
	ds_read_b128 v[204:207], v185 offset:53248
	ds_read_b128 v[208:211], v185 offset:53264
	ds_read_b128 v[212:215], v185 offset:55296
	ds_read_b128 v[216:219], v185 offset:55312
	global_load_lds_dwordx4 v[174:175], off
	s_add_i32 m0, s22, 0x2000
	s_add_u32 s0, s0, 0x80080
	v_lshl_add_u64 v[174:175], v[176:177], 0, s[6:7]
	s_addc_u32 s1, s1, 0
	s_add_i32 s22, s31, s37
	global_load_lds_dwordx4 v[174:175], off
	v_lshl_add_u64 v[174:175], s[0:1], 0, v[168:169]
	s_mov_b32 m0, s22
	s_nop 0
	global_load_lds_dwordx4 v[174:175], off
	v_lshl_add_u64 v[174:175], s[0:1], 0, v[170:171]
	s_add_i32 m0, s22, 0x2000
	s_nop 0
	global_load_lds_dwordx4 v[174:175], off
	v_lshl_add_u64 v[174:175], v[178:179], 0, s[6:7]
	s_mov_b32 m0, s44
	s_nop 0
	global_load_lds_dwordx4 v[174:175], off
	v_lshl_add_u64 v[174:175], v[180:181], 0, s[6:7]
	s_mov_b32 m0, s45
	s_nop 0
	global_load_lds_dwordx4 v[174:175], off
	s_waitcnt vmcnt(8)
	s_waitcnt lgkmcnt(0)
	s_barrier
	s_setprio 1
	s_waitcnt lgkmcnt(0)
	v_mfma_scale_f32_16x16x128_f8f6f4 v[94:97], v[2:9], v[188:195], v[94:97], v186, v186 op_sel_hi:[0,0,0]
	v_mfma_scale_f32_16x16x128_f8f6f4 v[90:93], v[10:17], v[188:195], v[90:93], v186, v186 op_sel_hi:[0,0,0]
	v_mfma_scale_f32_16x16x128_f8f6f4 v[78:81], v[2:9], v[196:203], v[78:81], v186, v186 op_sel_hi:[0,0,0]
	v_mfma_scale_f32_16x16x128_f8f6f4 v[74:77], v[10:17], v[196:203], v[74:77], v186, v186 op_sel_hi:[0,0,0]
	v_mfma_scale_f32_16x16x128_f8f6f4 v[62:65], v[2:9], v[204:211], v[62:65], v186, v186 op_sel_hi:[0,0,0]
	v_mfma_scale_f32_16x16x128_f8f6f4 v[58:61], v[10:17], v[204:211], v[58:61], v186, v186 op_sel_hi:[0,0,0]
	v_mfma_scale_f32_16x16x128_f8f6f4 v[46:49], v[2:9], v[212:219], v[46:49], v186, v186 op_sel_hi:[0,0,0]
	v_mfma_scale_f32_16x16x128_f8f6f4 v[42:45], v[10:17], v[212:219], v[42:45], v186, v186 op_sel_hi:[0,0,0]
	s_setprio 0
	s_setprio 1
	v_mfma_scale_f32_16x16x128_f8f6f4 v[86:89], v[18:25], v[188:195], v[86:89], v186, v186 op_sel_hi:[0,0,0]
	v_mfma_scale_f32_16x16x128_f8f6f4 v[82:85], v[26:33], v[188:195], v[82:85], v186, v186 op_sel_hi:[0,0,0]
	v_mfma_scale_f32_16x16x128_f8f6f4 v[70:73], v[18:25], v[196:203], v[70:73], v186, v186 op_sel_hi:[0,0,0]
	v_mfma_scale_f32_16x16x128_f8f6f4 v[66:69], v[26:33], v[196:203], v[66:69], v186, v186 op_sel_hi:[0,0,0]
	v_mfma_scale_f32_16x16x128_f8f6f4 v[54:57], v[18:25], v[204:211], v[54:57], v186, v186 op_sel_hi:[0,0,0]
	v_mfma_scale_f32_16x16x128_f8f6f4 v[50:53], v[26:33], v[204:211], v[50:53], v186, v186 op_sel_hi:[0,0,0]
	v_mfma_scale_f32_16x16x128_f8f6f4 v[38:41], v[18:25], v[212:219], v[38:41], v186, v186 op_sel_hi:[0,0,0]
	v_mfma_scale_f32_16x16x128_f8f6f4 v[34:37], v[26:33], v[212:219], v[34:37], v186, v186 op_sel_hi:[0,0,0]
	s_setprio 0
	s_barrier
	s_add_i32 s29, s29, 2
	s_add_u32 s20, s20, 0x100
	s_addc_u32 s21, s21, 0
	s_add_u32 s27, s27, 0x100
	s_addc_u32 s28, s28, 0
	s_cmp_gt_u32 s29, 29
	s_cbranch_scc0 .LBB0_271
	s_and_b64 vcc, exec, s[8:9]
	s_cbranch_vccz .LBB0_274
	s_barrier

.LBB0_839:
	ds_read_b128 v[26:29], v183
	ds_read_b128 v[30:33], v183 offset:16
	ds_read_b128 v[18:21], v183 offset:2048
	ds_read_b128 v[22:25], v183 offset:2064
	ds_read_b128 v[10:13], v184
	ds_read_b128 v[14:17], v184 offset:16
	ds_read_b128 v[2:5], v184 offset:2048
	ds_read_b128 v[6:9], v184 offset:2064
	s_add_u32 s30, s28, 0xfffc0080
	s_addc_u32 s31, s29, -1
	s_cmp_eq_u32 s53, 12
	s_cselect_b32 s35, s21, s31
	s_cselect_b32 s34, s49, s30
	s_cselect_b32 s31, s19, s52
	s_cselect_b32 s30, s50, s51
	v_lshl_add_u64 v[212:213], s[28:29], 0, v[162:163]
	s_add_i32 m0, s27, 0xc000
	ds_read_b128 v[174:177], v185
	ds_read_b128 v[178:181], v185 offset:16
	ds_read_b128 v[188:191], v185 offset:2048
	ds_read_b128 v[192:195], v185 offset:2064
	ds_read_b128 v[196:199], v185 offset:4096
	ds_read_b128 v[200:203], v185 offset:4112
	ds_read_b128 v[204:207], v185 offset:6144
	ds_read_b128 v[208:211], v185 offset:6160
	global_load_lds_dwordx4 v[212:213], off
	v_lshl_add_u64 v[212:213], s[28:29], 0, v[172:173]
	s_add_i32 m0, s27, 0xe000
	s_nop 0
	global_load_lds_dwordx4 v[212:213], off
	s_waitcnt vmcnt(8)
	s_waitcnt lgkmcnt(0)
	s_barrier
	s_setprio 1
	s_waitcnt lgkmcnt(0)
	v_mfma_scale_f32_16x16x128_f8f6f4 v[158:161], v[26:33], v[174:181], v[158:161], v186, v186 op_sel_hi:[0,0,0]
	v_mfma_scale_f32_16x16x128_f8f6f4 v[154:157], v[18:25], v[174:181], v[154:157], v186, v186 op_sel_hi:[0,0,0]
	v_mfma_scale_f32_16x16x128_f8f6f4 v[142:145], v[26:33], v[188:195], v[142:145], v186, v186 op_sel_hi:[0,0,0]
	v_mfma_scale_f32_16x16x128_f8f6f4 v[138:141], v[18:25], v[188:195], v[138:141], v186, v186 op_sel_hi:[0,0,0]
	v_mfma_scale_f32_16x16x128_f8f6f4 v[126:129], v[26:33], v[196:203], v[126:129], v186, v186 op_sel_hi:[0,0,0]
	v_mfma_scale_f32_16x16x128_f8f6f4 v[122:125], v[18:25], v[196:203], v[122:125], v186, v186 op_sel_hi:[0,0,0]
	v_mfma_scale_f32_16x16x128_f8f6f4 v[110:113], v[26:33], v[204:211], v[110:113], v186, v186 op_sel_hi:[0,0,0]
	v_mfma_scale_f32_16x16x128_f8f6f4 v[106:109], v[18:25], v[204:211], v[106:109], v186, v186 op_sel_hi:[0,0,0]
	s_setprio 0
	s_setprio 1
	v_mfma_scale_f32_16x16x128_f8f6f4 v[150:153], v[10:17], v[174:181], v[150:153], v186, v186 op_sel_hi:[0,0,0]
	v_mfma_scale_f32_16x16x128_f8f6f4 v[146:149], v[2:9], v[174:181], v[146:149], v186, v186 op_sel_hi:[0,0,0]
	v_mfma_scale_f32_16x16x128_f8f6f4 v[134:137], v[10:17], v[188:195], v[134:137], v186, v186 op_sel_hi:[0,0,0]
	v_mfma_scale_f32_16x16x128_f8f6f4 v[130:133], v[2:9], v[188:195], v[130:133], v186, v186 op_sel_hi:[0,0,0]
	v_mfma_scale_f32_16x16x128_f8f6f4 v[118:121], v[10:17], v[196:203], v[118:121], v186, v186 op_sel_hi:[0,0,0]
	v_mfma_scale_f32_16x16x128_f8f6f4 v[114:117], v[2:9], v[196:203], v[114:117], v186, v186 op_sel_hi:[0,0,0]
	v_mfma_scale_f32_16x16x128_f8f6f4 v[102:105], v[10:17], v[204:211], v[102:105], v186, v186 op_sel_hi:[0,0,0]
	v_mfma_scale_f32_16x16x128_f8f6f4 v[98:101], v[2:9], v[204:211], v[98:101], v186, v186 op_sel_hi:[0,0,0]
	s_setprio 0
	s_barrier
	s_add_i32 s54, s46, s36
	v_lshl_add_u64 v[174:175], s[30:31], 0, v[168:169]
	s_mov_b32 m0, s54
	ds_read_b128 v[188:191], v185 offset:16384
	ds_read_b128 v[192:195], v185 offset:16400
	ds_read_b128 v[196:199], v185 offset:18432
	ds_read_b128 v[200:203], v185 offset:18448
	ds_read_b128 v[204:207], v185 offset:20480
	ds_read_b128 v[208:211], v185 offset:20496
	ds_read_b128 v[212:215], v185 offset:22528
	ds_read_b128 v[216:219], v185 offset:22544
	global_load_lds_dwordx4 v[174:175], off
	s_add_i32 m0, s54, 0x2000
	s_add_u32 s54, s30, 0x40000
	v_lshl_add_u64 v[176:177], s[30:31], 0, v[170:171]
	s_addc_u32 s55, s31, 0
	s_add_i32 s56, s47, s36
	global_load_lds_dwordx4 v[176:177], off
	v_lshl_add_u64 v[178:179], s[54:55], 0, v[168:169]
	s_mov_b32 m0, s56
	v_lshl_add_u64 v[180:181], s[34:35], 0, v[172:173]
	global_load_lds_dwordx4 v[178:179], off
	v_lshl_add_u64 v[178:179], s[54:55], 0, v[170:171]
	s_add_i32 m0, s56, 0x2000
	s_nop 0
	global_load_lds_dwordx4 v[178:179], off
	v_lshl_add_u64 v[178:179], s[34:35], 0, v[162:163]
	s_mov_b32 m0, s27
	s_nop 0
	global_load_lds_dwordx4 v[178:179], off
	s_mov_b32 m0, s37
	s_nop 0
	global_load_lds_dwordx4 v[180:181], off
	s_waitcnt vmcnt(8)
	s_waitcnt lgkmcnt(0)
	s_barrier
	s_setprio 1
	s_waitcnt lgkmcnt(0)
	v_mfma_scale_f32_16x16x128_f8f6f4 v[94:97], v[26:33], v[188:195], v[94:97], v186, v186 op_sel_hi:[0,0,0]
	v_mfma_scale_f32_16x16x128_f8f6f4 v[90:93], v[18:25], v[188:195], v[90:93], v186, v186 op_sel_hi:[0,0,0]
	v_mfma_scale_f32_16x16x128_f8f6f4 v[78:81], v[26:33], v[196:203], v[78:81], v186, v186 op_sel_hi:[0,0,0]
	v_mfma_scale_f32_16x16x128_f8f6f4 v[74:77], v[18:25], v[196:203], v[74:77], v186, v186 op_sel_hi:[0,0,0]
	v_mfma_scale_f32_16x16x128_f8f6f4 v[62:65], v[26:33], v[204:211], v[62:65], v186, v186 op_sel_hi:[0,0,0]
	v_mfma_scale_f32_16x16x128_f8f6f4 v[58:61], v[18:25], v[204:211], v[58:61], v186, v186 op_sel_hi:[0,0,0]
	v_mfma_scale_f32_16x16x128_f8f6f4 v[46:49], v[26:33], v[212:219], v[46:49], v186, v186 op_sel_hi:[0,0,0]
	v_mfma_scale_f32_16x16x128_f8f6f4 v[42:45], v[18:25], v[212:219], v[42:45], v186, v186 op_sel_hi:[0,0,0]
	s_setprio 0
	s_setprio 1
	v_mfma_scale_f32_16x16x128_f8f6f4 v[86:89], v[10:17], v[188:195], v[86:89], v186, v186 op_sel_hi:[0,0,0]
	v_mfma_scale_f32_16x16x128_f8f6f4 v[82:85], v[2:9], v[188:195], v[82:85], v186, v186 op_sel_hi:[0,0,0]
	v_mfma_scale_f32_16x16x128_f8f6f4 v[70:73], v[10:17], v[196:203], v[70:73], v186, v186 op_sel_hi:[0,0,0]
	v_mfma_scale_f32_16x16x128_f8f6f4 v[66:69], v[2:9], v[196:203], v[66:69], v186, v186 op_sel_hi:[0,0,0]
	v_mfma_scale_f32_16x16x128_f8f6f4 v[54:57], v[10:17], v[204:211], v[54:57], v186, v186 op_sel_hi:[0,0,0]
	v_mfma_scale_f32_16x16x128_f8f6f4 v[50:53], v[2:9], v[204:211], v[50:53], v186, v186 op_sel_hi:[0,0,0]
	v_mfma_scale_f32_16x16x128_f8f6f4 v[38:41], v[10:17], v[212:219], v[38:41], v186, v186 op_sel_hi:[0,0,0]
	v_mfma_scale_f32_16x16x128_f8f6f4 v[34:37], v[2:9], v[212:219], v[34:37], v186, v186 op_sel_hi:[0,0,0]
	s_setprio 0
	s_barrier
	s_add_i32 s54, 0, 0x18000
	s_add_i32 s55, 0, 0x1c000
	v_add_u32_e32 v14, s54, v182
	v_add_u32_e32 v30, s55, v182
	ds_read_b128 v[2:5], v14
	ds_read_b128 v[6:9], v14 offset:16
	ds_read_b128 v[10:13], v14 offset:2048
	ds_read_b128 v[14:17], v14 offset:2064
	ds_read_b128 v[18:21], v30
	ds_read_b128 v[22:25], v30 offset:16
	ds_read_b128 v[26:29], v30 offset:2048
	ds_read_b128 v[30:33], v30 offset:2064
	s_add_u32 s34, s34, 0x40000
	s_addc_u32 s35, s35, 0
	s_mov_b32 m0, s38
	v_lshl_add_u64 v[220:221], s[34:35], 0, v[162:163]
	ds_read_b128 v[188:191], v185 offset:32768
	ds_read_b128 v[192:195], v185 offset:32784
	ds_read_b128 v[196:199], v185 offset:34816
	ds_read_b128 v[200:203], v185 offset:34832
	ds_read_b128 v[204:207], v185 offset:36864
	ds_read_b128 v[208:211], v185 offset:36880
	ds_read_b128 v[212:215], v185 offset:38912
	ds_read_b128 v[216:219], v185 offset:38928
	global_load_lds_dwordx4 v[220:221], off
	v_lshl_add_u64 v[220:221], s[34:35], 0, v[172:173]
	s_mov_b32 m0, s39
	s_nop 0
	global_load_lds_dwordx4 v[220:221], off
	s_waitcnt vmcnt(8)
	s_waitcnt lgkmcnt(0)
	s_barrier
	s_setprio 1
	s_waitcnt lgkmcnt(0)
	v_mfma_scale_f32_16x16x128_f8f6f4 v[158:161], v[2:9], v[188:195], v[158:161], v186, v186 op_sel_hi:[0,0,0]
	v_mfma_scale_f32_16x16x128_f8f6f4 v[154:157], v[10:17], v[188:195], v[154:157], v186, v186 op_sel_hi:[0,0,0]
	v_mfma_scale_f32_16x16x128_f8f6f4 v[142:145], v[2:9], v[196:203], v[142:145], v186, v186 op_sel_hi:[0,0,0]
	v_mfma_scale_f32_16x16x128_f8f6f4 v[138:141], v[10:17], v[196:203], v[138:141], v186, v186 op_sel_hi:[0,0,0]
	v_mfma_scale_f32_16x16x128_f8f6f4 v[126:129], v[2:9], v[204:211], v[126:129], v186, v186 op_sel_hi:[0,0,0]
	v_mfma_scale_f32_16x16x128_f8f6f4 v[122:125], v[10:17], v[204:211], v[122:125], v186, v186 op_sel_hi:[0,0,0]
	v_mfma_scale_f32_16x16x128_f8f6f4 v[110:113], v[2:9], v[212:219], v[110:113], v186, v186 op_sel_hi:[0,0,0]
	v_mfma_scale_f32_16x16x128_f8f6f4 v[106:109], v[10:17], v[212:219], v[106:109], v186, v186 op_sel_hi:[0,0,0]
	s_setprio 0
	s_setprio 1
	v_mfma_scale_f32_16x16x128_f8f6f4 v[150:153], v[18:25], v[188:195], v[150:153], v186, v186 op_sel_hi:[0,0,0]
	v_mfma_scale_f32_16x16x128_f8f6f4 v[146:149], v[26:33], v[188:195], v[146:149], v186, v186 op_sel_hi:[0,0,0]
	v_mfma_scale_f32_16x16x128_f8f6f4 v[134:137], v[18:25], v[196:203], v[134:137], v186, v186 op_sel_hi:[0,0,0]
	v_mfma_scale_f32_16x16x128_f8f6f4 v[130:133], v[26:33], v[196:203], v[130:133], v186, v186 op_sel_hi:[0,0,0]
	v_mfma_scale_f32_16x16x128_f8f6f4 v[118:121], v[18:25], v[204:211], v[118:121], v186, v186 op_sel_hi:[0,0,0]
	v_mfma_scale_f32_16x16x128_f8f6f4 v[114:117], v[26:33], v[204:211], v[114:117], v186, v186 op_sel_hi:[0,0,0]
	v_mfma_scale_f32_16x16x128_f8f6f4 v[102:105], v[18:25], v[212:219], v[102:105], v186, v186 op_sel_hi:[0,0,0]
	v_mfma_scale_f32_16x16x128_f8f6f4 v[98:101], v[26:33], v[212:219], v[98:101], v186, v186 op_sel_hi:[0,0,0]
	s_setprio 0
	s_barrier
	s_add_i32 s34, s54, s36
	v_lshl_add_u64 v[174:175], v[174:175], 0, s[8:9]
	s_mov_b32 m0, s34
	ds_read_b128 v[188:191], v185 offset:49152
	ds_read_b128 v[192:195], v185 offset:49168
	ds_read_b128 v[196:199], v185 offset:51200
	ds_read_b128 v[200:203], v185 offset:51216
	ds_read_b128 v[204:207], v185 offset:53248
	ds_read_b128 v[208:211], v185 offset:53264
	ds_read_b128 v[212:215], v185 offset:55296
	ds_read_b128 v[216:219], v185 offset:55312
	global_load_lds_dwordx4 v[174:175], off
	s_add_i32 m0, s34, 0x2000
	s_add_u32 s30, s30, 0x40080
	v_lshl_add_u64 v[174:175], v[176:177], 0, s[8:9]
	s_addc_u32 s31, s31, 0
	s_add_i32 s34, s55, s36
	global_load_lds_dwordx4 v[174:175], off
	v_lshl_add_u64 v[174:175], s[30:31], 0, v[168:169]
	s_mov_b32 m0, s34
	s_nop 0
	global_load_lds_dwordx4 v[174:175], off
	v_lshl_add_u64 v[174:175], s[30:31], 0, v[170:171]
	s_add_i32 m0, s34, 0x2000
	s_nop 0
	global_load_lds_dwordx4 v[174:175], off
	v_lshl_add_u64 v[174:175], v[178:179], 0, s[8:9]
	s_mov_b32 m0, s43
	s_nop 0
	global_load_lds_dwordx4 v[174:175], off
	v_lshl_add_u64 v[174:175], v[180:181], 0, s[8:9]
	s_mov_b32 m0, s44
	s_nop 0
	global_load_lds_dwordx4 v[174:175], off
	s_waitcnt vmcnt(8)
	s_waitcnt lgkmcnt(0)
	s_barrier
	s_setprio 1
	s_waitcnt lgkmcnt(0)
	v_mfma_scale_f32_16x16x128_f8f6f4 v[94:97], v[2:9], v[188:195], v[94:97], v186, v186 op_sel_hi:[0,0,0]
	v_mfma_scale_f32_16x16x128_f8f6f4 v[90:93], v[10:17], v[188:195], v[90:93], v186, v186 op_sel_hi:[0,0,0]
	v_mfma_scale_f32_16x16x128_f8f6f4 v[78:81], v[2:9], v[196:203], v[78:81], v186, v186 op_sel_hi:[0,0,0]
	v_mfma_scale_f32_16x16x128_f8f6f4 v[74:77], v[10:17], v[196:203], v[74:77], v186, v186 op_sel_hi:[0,0,0]
	v_mfma_scale_f32_16x16x128_f8f6f4 v[62:65], v[2:9], v[204:211], v[62:65], v186, v186 op_sel_hi:[0,0,0]
	v_mfma_scale_f32_16x16x128_f8f6f4 v[58:61], v[10:17], v[204:211], v[58:61], v186, v186 op_sel_hi:[0,0,0]
	v_mfma_scale_f32_16x16x128_f8f6f4 v[46:49], v[2:9], v[212:219], v[46:49], v186, v186 op_sel_hi:[0,0,0]
	v_mfma_scale_f32_16x16x128_f8f6f4 v[42:45], v[10:17], v[212:219], v[42:45], v186, v186 op_sel_hi:[0,0,0]
	s_setprio 0
	s_setprio 1
	v_mfma_scale_f32_16x16x128_f8f6f4 v[86:89], v[18:25], v[188:195], v[86:89], v186, v186 op_sel_hi:[0,0,0]
	v_mfma_scale_f32_16x16x128_f8f6f4 v[82:85], v[26:33], v[188:195], v[82:85], v186, v186 op_sel_hi:[0,0,0]
	v_mfma_scale_f32_16x16x128_f8f6f4 v[70:73], v[18:25], v[196:203], v[70:73], v186, v186 op_sel_hi:[0,0,0]
	v_mfma_scale_f32_16x16x128_f8f6f4 v[66:69], v[26:33], v[196:203], v[66:69], v186, v186 op_sel_hi:[0,0,0]
	v_mfma_scale_f32_16x16x128_f8f6f4 v[54:57], v[18:25], v[204:211], v[54:57], v186, v186 op_sel_hi:[0,0,0]
	v_mfma_scale_f32_16x16x128_f8f6f4 v[50:53], v[26:33], v[204:211], v[50:53], v186, v186 op_sel_hi:[0,0,0]
	v_mfma_scale_f32_16x16x128_f8f6f4 v[38:41], v[18:25], v[212:219], v[38:41], v186, v186 op_sel_hi:[0,0,0]
	v_mfma_scale_f32_16x16x128_f8f6f4 v[34:37], v[26:33], v[212:219], v[34:37], v186, v186 op_sel_hi:[0,0,0]
	s_setprio 0
	s_barrier
	s_add_i32 s53, s53, 2
	s_add_u32 s28, s28, 0x100
	s_addc_u32 s29, s29, 0
	s_add_u32 s51, s51, 0x100
	s_addc_u32 s52, s52, 0
	s_cmp_gt_u32 s53, 13
	s_cbranch_scc0 .LBB0_839
	s_and_b64 vcc, exec, s[10:11]
	s_cbranch_vccz .LBB0_842
	s_barrier

.LBB0_863:
	ds_read_b128 v[146:149], v154
	ds_read_b128 v[158:161], v154 offset:1024
	ds_read_b128 v[162:165], v154 offset:2048
	ds_read_b128 v[166:169], v154 offset:3072
	ds_read_b128 v[170:173], v155
	ds_read_b128 v[174:177], v155 offset:1024
	ds_read_b128 v[178:181], v155 offset:2048
	ds_read_b128 v[182:185], v155 offset:3072
	s_add_u32 s22, s20, 0xfff80080
	s_addc_u32 s23, s21, -1
	s_cmp_eq_u32 s43, 28
	s_cselect_b32 s25, s13, s23
	s_cselect_b32 s24, s39, s22
	s_cselect_b32 s23, s11, s42
	s_cselect_b32 s22, s40, s41
	v_lshl_add_u64 v[150:151], s[20:21], 0, v[138:139]
	s_add_i32 m0, s19, 0xc000
	ds_read_b128 v[186:189], v156
	ds_read_b128 v[190:193], v156 offset:1024
	ds_read_b128 v[194:197], v156 offset:2048
	ds_read_b128 v[198:201], v156 offset:3072
	ds_read_b128 v[202:205], v156 offset:4096
	ds_read_b128 v[206:209], v156 offset:5120
	ds_read_b128 v[210:213], v156 offset:6144
	ds_read_b128 v[214:217], v156 offset:7168
	global_load_lds_dwordx4 v[150:151], off
	v_lshl_add_u64 v[150:151], s[20:21], 0, v[140:141]
	s_add_i32 m0, s19, 0xe000
	s_nop 0
	global_load_lds_dwordx4 v[150:151], off
	s_waitcnt vmcnt(8)
	s_waitcnt lgkmcnt(0)
	s_barrier
	s_setprio 1
	s_waitcnt lgkmcnt(0)
	v_mfma_f32_16x16x32_bf16 v[126:129], v[146:149], v[186:189], v[126:129]
	v_mfma_f32_16x16x32_bf16 v[122:125], v[162:165], v[186:189], v[122:125]
	v_mfma_f32_16x16x32_bf16 v[110:113], v[146:149], v[194:197], v[110:113]
	v_mfma_f32_16x16x32_bf16 v[106:109], v[162:165], v[194:197], v[106:109]
	v_mfma_f32_16x16x32_bf16 v[94:97], v[146:149], v[202:205], v[94:97]
	v_mfma_f32_16x16x32_bf16 v[90:93], v[162:165], v[202:205], v[90:93]
	v_mfma_f32_16x16x32_bf16 v[78:81], v[146:149], v[210:213], v[78:81]
	v_mfma_f32_16x16x32_bf16 v[74:77], v[162:165], v[210:213], v[74:77]
	v_mfma_f32_16x16x32_bf16 v[126:129], v[158:161], v[190:193], v[126:129]
	v_mfma_f32_16x16x32_bf16 v[122:125], v[166:169], v[190:193], v[122:125]
	v_mfma_f32_16x16x32_bf16 v[110:113], v[158:161], v[198:201], v[110:113]
	v_mfma_f32_16x16x32_bf16 v[106:109], v[166:169], v[198:201], v[106:109]
	v_mfma_f32_16x16x32_bf16 v[94:97], v[158:161], v[206:209], v[94:97]
	v_mfma_f32_16x16x32_bf16 v[90:93], v[166:169], v[206:209], v[90:93]
	v_mfma_f32_16x16x32_bf16 v[78:81], v[158:161], v[214:217], v[78:81]
	v_mfma_f32_16x16x32_bf16 v[74:77], v[166:169], v[214:217], v[74:77]
	s_setprio 0
	s_setprio 1
	v_mfma_f32_16x16x32_bf16 v[118:121], v[170:173], v[186:189], v[118:121]
	v_mfma_f32_16x16x32_bf16 v[114:117], v[178:181], v[186:189], v[114:117]
	v_mfma_f32_16x16x32_bf16 v[102:105], v[170:173], v[194:197], v[102:105]
	v_mfma_f32_16x16x32_bf16 v[98:101], v[178:181], v[194:197], v[98:101]
	v_mfma_f32_16x16x32_bf16 v[86:89], v[170:173], v[202:205], v[86:89]
	v_mfma_f32_16x16x32_bf16 v[82:85], v[178:181], v[202:205], v[82:85]
	v_mfma_f32_16x16x32_bf16 v[70:73], v[170:173], v[210:213], v[70:73]
	v_mfma_f32_16x16x32_bf16 v[66:69], v[178:181], v[210:213], v[66:69]
	v_mfma_f32_16x16x32_bf16 v[118:121], v[174:177], v[190:193], v[118:121]
	v_mfma_f32_16x16x32_bf16 v[114:117], v[182:185], v[190:193], v[114:117]
	v_mfma_f32_16x16x32_bf16 v[102:105], v[174:177], v[198:201], v[102:105]
	v_mfma_f32_16x16x32_bf16 v[98:101], v[182:185], v[198:201], v[98:101]
	v_mfma_f32_16x16x32_bf16 v[86:89], v[174:177], v[206:209], v[86:89]
	v_mfma_f32_16x16x32_bf16 v[82:85], v[182:185], v[206:209], v[82:85]
	v_mfma_f32_16x16x32_bf16 v[70:73], v[174:177], v[214:217], v[70:73]
	v_mfma_f32_16x16x32_bf16 v[66:69], v[182:185], v[214:217], v[66:69]
	s_setprio 0
	s_barrier
	s_add_i32 s44, s36, s27
	v_lshl_add_u64 v[150:151], s[22:23], 0, v[132:133]
	s_mov_b32 m0, s44
	ds_read_b128 v[186:189], v156 offset:16384
	ds_read_b128 v[190:193], v156 offset:17408
	ds_read_b128 v[194:197], v156 offset:18432
	ds_read_b128 v[198:201], v156 offset:19456
	ds_read_b128 v[202:205], v156 offset:20480
	ds_read_b128 v[206:209], v156 offset:21504
	ds_read_b128 v[210:213], v156 offset:22528
	ds_read_b128 v[214:217], v156 offset:23552
	global_load_lds_dwordx4 v[150:151], off
	s_add_i32 m0, s44, 0x2000
	s_add_u32 s44, s22, 0x80000
	v_lshl_add_u64 v[218:219], s[22:23], 0, v[136:137]
	s_addc_u32 s45, s23, 0
	s_add_i32 s46, s37, s27
	global_load_lds_dwordx4 v[218:219], off
	v_lshl_add_u64 v[220:221], s[44:45], 0, v[132:133]
	s_mov_b32 m0, s46
	v_lshl_add_u64 v[222:223], s[24:25], 0, v[134:135]
	global_load_lds_dwordx4 v[220:221], off
	v_lshl_add_u64 v[220:221], s[44:45], 0, v[136:137]
	s_add_i32 m0, s46, 0x2000
	s_nop 0
	global_load_lds_dwordx4 v[220:221], off
	v_lshl_add_u64 v[220:221], s[24:25], 0, v[130:131]
	s_mov_b32 m0, s19
	s_nop 0
	global_load_lds_dwordx4 v[220:221], off
	s_mov_b32 m0, s28
	s_nop 0
	global_load_lds_dwordx4 v[222:223], off
	s_waitcnt vmcnt(8)
	s_waitcnt lgkmcnt(0)
	s_barrier
	s_setprio 1
	s_waitcnt lgkmcnt(0)
	v_mfma_f32_16x16x32_bf16 v[62:65], v[146:149], v[186:189], v[62:65]
	v_mfma_f32_16x16x32_bf16 v[58:61], v[162:165], v[186:189], v[58:61]
	v_mfma_f32_16x16x32_bf16 v[46:49], v[146:149], v[194:197], v[46:49]
	v_mfma_f32_16x16x32_bf16 v[42:45], v[162:165], v[194:197], v[42:45]
	v_mfma_f32_16x16x32_bf16 v[30:33], v[146:149], v[202:205], v[30:33]
	v_mfma_f32_16x16x32_bf16 v[26:29], v[162:165], v[202:205], v[26:29]
	v_mfma_f32_16x16x32_bf16 v[14:17], v[146:149], v[210:213], v[14:17]
	v_mfma_f32_16x16x32_bf16 v[10:13], v[162:165], v[210:213], v[10:13]
	v_mfma_f32_16x16x32_bf16 v[62:65], v[158:161], v[190:193], v[62:65]
	v_mfma_f32_16x16x32_bf16 v[58:61], v[166:169], v[190:193], v[58:61]
	v_mfma_f32_16x16x32_bf16 v[46:49], v[158:161], v[198:201], v[46:49]
	v_mfma_f32_16x16x32_bf16 v[42:45], v[166:169], v[198:201], v[42:45]
	v_mfma_f32_16x16x32_bf16 v[30:33], v[158:161], v[206:209], v[30:33]
	v_mfma_f32_16x16x32_bf16 v[26:29], v[166:169], v[206:209], v[26:29]
	v_mfma_f32_16x16x32_bf16 v[14:17], v[158:161], v[214:217], v[14:17]
	v_mfma_f32_16x16x32_bf16 v[10:13], v[166:169], v[214:217], v[10:13]
	s_setprio 0
	s_setprio 1
	v_mfma_f32_16x16x32_bf16 v[54:57], v[170:173], v[186:189], v[54:57]
	v_mfma_f32_16x16x32_bf16 v[50:53], v[178:181], v[186:189], v[50:53]
	v_mfma_f32_16x16x32_bf16 v[38:41], v[170:173], v[194:197], v[38:41]
	v_mfma_f32_16x16x32_bf16 v[34:37], v[178:181], v[194:197], v[34:37]
	v_mfma_f32_16x16x32_bf16 v[22:25], v[170:173], v[202:205], v[22:25]
	v_mfma_f32_16x16x32_bf16 v[18:21], v[178:181], v[202:205], v[18:21]
	v_mfma_f32_16x16x32_bf16 v[6:9], v[170:173], v[210:213], v[6:9]
	v_mfma_f32_16x16x32_bf16 v[2:5], v[178:181], v[210:213], v[2:5]
	v_mfma_f32_16x16x32_bf16 v[54:57], v[174:177], v[190:193], v[54:57]
	v_mfma_f32_16x16x32_bf16 v[50:53], v[182:185], v[190:193], v[50:53]
	v_mfma_f32_16x16x32_bf16 v[38:41], v[174:177], v[198:201], v[38:41]
	v_mfma_f32_16x16x32_bf16 v[34:37], v[182:185], v[198:201], v[34:37]
	v_mfma_f32_16x16x32_bf16 v[22:25], v[174:177], v[206:209], v[22:25]
	v_mfma_f32_16x16x32_bf16 v[18:21], v[182:185], v[206:209], v[18:21]
	v_mfma_f32_16x16x32_bf16 v[6:9], v[174:177], v[214:217], v[6:9]
	v_mfma_f32_16x16x32_bf16 v[2:5], v[182:185], v[214:217], v[2:5]
	s_setprio 0
	s_barrier
	s_add_i32 s44, 0, 0x18000
	v_add_u32_e32 v157, s44, v152
	s_add_i32 s45, 0, 0x1c000
	ds_read_b128 v[146:149], v157
	ds_read_b128 v[158:161], v157 offset:1024
	ds_read_b128 v[162:165], v157 offset:2048
	ds_read_b128 v[166:169], v157 offset:3072
	v_add_u32_e32 v157, s45, v152
	ds_read_b128 v[170:173], v157
	ds_read_b128 v[174:177], v157 offset:1024
	ds_read_b128 v[178:181], v157 offset:2048
	ds_read_b128 v[182:185], v157 offset:3072
	s_add_u32 s24, s24, 0x80000
	s_addc_u32 s25, s25, 0
	s_mov_b32 m0, s29
	v_lshl_add_u64 v[224:225], s[24:25], 0, v[130:131]
	ds_read_b128 v[186:189], v156 offset:32768
	ds_read_b128 v[190:193], v156 offset:33792
	ds_read_b128 v[194:197], v156 offset:34816
	ds_read_b128 v[198:201], v156 offset:35840
	ds_read_b128 v[202:205], v156 offset:36864
	ds_read_b128 v[206:209], v156 offset:37888
	ds_read_b128 v[210:213], v156 offset:38912
	ds_read_b128 v[214:217], v156 offset:39936
	global_load_lds_dwordx4 v[224:225], off
	v_lshl_add_u64 v[224:225], s[24:25], 0, v[134:135]
	s_mov_b32 m0, s30
	s_nop 0
	global_load_lds_dwordx4 v[224:225], off
	s_waitcnt vmcnt(8)
	s_waitcnt lgkmcnt(0)
	s_barrier
	s_setprio 1
	s_waitcnt lgkmcnt(0)
	v_mfma_f32_16x16x32_bf16 v[126:129], v[146:149], v[186:189], v[126:129]
	v_mfma_f32_16x16x32_bf16 v[122:125], v[162:165], v[186:189], v[122:125]
	v_mfma_f32_16x16x32_bf16 v[110:113], v[146:149], v[194:197], v[110:113]
	v_mfma_f32_16x16x32_bf16 v[106:109], v[162:165], v[194:197], v[106:109]
	v_mfma_f32_16x16x32_bf16 v[94:97], v[146:149], v[202:205], v[94:97]
	v_mfma_f32_16x16x32_bf16 v[90:93], v[162:165], v[202:205], v[90:93]
	v_mfma_f32_16x16x32_bf16 v[78:81], v[146:149], v[210:213], v[78:81]
	v_mfma_f32_16x16x32_bf16 v[74:77], v[162:165], v[210:213], v[74:77]
	v_mfma_f32_16x16x32_bf16 v[126:129], v[158:161], v[190:193], v[126:129]
	v_mfma_f32_16x16x32_bf16 v[122:125], v[166:169], v[190:193], v[122:125]
	v_mfma_f32_16x16x32_bf16 v[110:113], v[158:161], v[198:201], v[110:113]
	v_mfma_f32_16x16x32_bf16 v[106:109], v[166:169], v[198:201], v[106:109]
	v_mfma_f32_16x16x32_bf16 v[94:97], v[158:161], v[206:209], v[94:97]
	v_mfma_f32_16x16x32_bf16 v[90:93], v[166:169], v[206:209], v[90:93]
	v_mfma_f32_16x16x32_bf16 v[78:81], v[158:161], v[214:217], v[78:81]
	v_mfma_f32_16x16x32_bf16 v[74:77], v[166:169], v[214:217], v[74:77]
	s_setprio 0
	s_setprio 1
	v_mfma_f32_16x16x32_bf16 v[118:121], v[170:173], v[186:189], v[118:121]
	v_mfma_f32_16x16x32_bf16 v[114:117], v[178:181], v[186:189], v[114:117]
	v_mfma_f32_16x16x32_bf16 v[102:105], v[170:173], v[194:197], v[102:105]
	v_mfma_f32_16x16x32_bf16 v[98:101], v[178:181], v[194:197], v[98:101]
	v_mfma_f32_16x16x32_bf16 v[86:89], v[170:173], v[202:205], v[86:89]
	v_mfma_f32_16x16x32_bf16 v[82:85], v[178:181], v[202:205], v[82:85]
	v_mfma_f32_16x16x32_bf16 v[70:73], v[170:173], v[210:213], v[70:73]
	v_mfma_f32_16x16x32_bf16 v[66:69], v[178:181], v[210:213], v[66:69]
	v_mfma_f32_16x16x32_bf16 v[118:121], v[174:177], v[190:193], v[118:121]
	v_mfma_f32_16x16x32_bf16 v[114:117], v[182:185], v[190:193], v[114:117]
	v_mfma_f32_16x16x32_bf16 v[102:105], v[174:177], v[198:201], v[102:105]
	v_mfma_f32_16x16x32_bf16 v[98:101], v[182:185], v[198:201], v[98:101]
	v_mfma_f32_16x16x32_bf16 v[86:89], v[174:177], v[206:209], v[86:89]
	v_mfma_f32_16x16x32_bf16 v[82:85], v[182:185], v[206:209], v[82:85]
	v_mfma_f32_16x16x32_bf16 v[70:73], v[174:177], v[214:217], v[70:73]
	v_mfma_f32_16x16x32_bf16 v[66:69], v[182:185], v[214:217], v[66:69]
	s_setprio 0
	s_barrier
	s_add_i32 s24, s44, s27
	v_lshl_add_u64 v[150:151], v[150:151], 0, s[6:7]
	s_mov_b32 m0, s24
	ds_read_b128 v[186:189], v156 offset:49152
	ds_read_b128 v[190:193], v156 offset:50176
	ds_read_b128 v[194:197], v156 offset:51200
	ds_read_b128 v[198:201], v156 offset:52224
	ds_read_b128 v[202:205], v156 offset:53248
	ds_read_b128 v[206:209], v156 offset:54272
	ds_read_b128 v[210:213], v156 offset:55296
	ds_read_b128 v[214:217], v156 offset:56320
	global_load_lds_dwordx4 v[150:151], off
	s_add_i32 m0, s24, 0x2000
	s_add_u32 s22, s22, 0x80080
	v_lshl_add_u64 v[150:151], v[218:219], 0, s[6:7]
	s_addc_u32 s23, s23, 0
	s_add_i32 s24, s45, s27
	global_load_lds_dwordx4 v[150:151], off
	v_lshl_add_u64 v[150:151], s[22:23], 0, v[132:133]
	s_mov_b32 m0, s24
	s_nop 0
	global_load_lds_dwordx4 v[150:151], off
	v_lshl_add_u64 v[150:151], s[22:23], 0, v[136:137]
	s_add_i32 m0, s24, 0x2000
	s_nop 0
	global_load_lds_dwordx4 v[150:151], off
	v_lshl_add_u64 v[150:151], v[220:221], 0, s[6:7]
	s_mov_b32 m0, s33
	s_nop 0
	global_load_lds_dwordx4 v[150:151], off
	v_lshl_add_u64 v[150:151], v[222:223], 0, s[6:7]
	s_mov_b32 m0, s34
	s_nop 0
	global_load_lds_dwordx4 v[150:151], off
	s_waitcnt vmcnt(8)
	s_waitcnt lgkmcnt(0)
	s_barrier
	s_setprio 1
	s_waitcnt lgkmcnt(0)
	v_mfma_f32_16x16x32_bf16 v[62:65], v[146:149], v[186:189], v[62:65]
	v_mfma_f32_16x16x32_bf16 v[58:61], v[162:165], v[186:189], v[58:61]
	v_mfma_f32_16x16x32_bf16 v[46:49], v[146:149], v[194:197], v[46:49]
	v_mfma_f32_16x16x32_bf16 v[42:45], v[162:165], v[194:197], v[42:45]
	v_mfma_f32_16x16x32_bf16 v[30:33], v[146:149], v[202:205], v[30:33]
	v_mfma_f32_16x16x32_bf16 v[26:29], v[162:165], v[202:205], v[26:29]
	v_mfma_f32_16x16x32_bf16 v[14:17], v[146:149], v[210:213], v[14:17]
	v_mfma_f32_16x16x32_bf16 v[10:13], v[162:165], v[210:213], v[10:13]
	v_mfma_f32_16x16x32_bf16 v[62:65], v[158:161], v[190:193], v[62:65]
	v_mfma_f32_16x16x32_bf16 v[58:61], v[166:169], v[190:193], v[58:61]
	v_mfma_f32_16x16x32_bf16 v[46:49], v[158:161], v[198:201], v[46:49]
	v_mfma_f32_16x16x32_bf16 v[42:45], v[166:169], v[198:201], v[42:45]
	v_mfma_f32_16x16x32_bf16 v[30:33], v[158:161], v[206:209], v[30:33]
	v_mfma_f32_16x16x32_bf16 v[26:29], v[166:169], v[206:209], v[26:29]
	v_mfma_f32_16x16x32_bf16 v[14:17], v[158:161], v[214:217], v[14:17]
	v_mfma_f32_16x16x32_bf16 v[10:13], v[166:169], v[214:217], v[10:13]
	s_setprio 0
	s_setprio 1
	v_mfma_f32_16x16x32_bf16 v[54:57], v[170:173], v[186:189], v[54:57]
	v_mfma_f32_16x16x32_bf16 v[50:53], v[178:181], v[186:189], v[50:53]
	v_mfma_f32_16x16x32_bf16 v[38:41], v[170:173], v[194:197], v[38:41]
	v_mfma_f32_16x16x32_bf16 v[34:37], v[178:181], v[194:197], v[34:37]
	v_mfma_f32_16x16x32_bf16 v[22:25], v[170:173], v[202:205], v[22:25]
	v_mfma_f32_16x16x32_bf16 v[18:21], v[178:181], v[202:205], v[18:21]
	v_mfma_f32_16x16x32_bf16 v[6:9], v[170:173], v[210:213], v[6:9]
	v_mfma_f32_16x16x32_bf16 v[2:5], v[178:181], v[210:213], v[2:5]
	v_mfma_f32_16x16x32_bf16 v[54:57], v[174:177], v[190:193], v[54:57]
	v_mfma_f32_16x16x32_bf16 v[50:53], v[182:185], v[190:193], v[50:53]
	v_mfma_f32_16x16x32_bf16 v[38:41], v[174:177], v[198:201], v[38:41]
	v_mfma_f32_16x16x32_bf16 v[34:37], v[182:185], v[198:201], v[34:37]
	v_mfma_f32_16x16x32_bf16 v[22:25], v[174:177], v[206:209], v[22:25]
	v_mfma_f32_16x16x32_bf16 v[18:21], v[182:185], v[206:209], v[18:21]
	v_mfma_f32_16x16x32_bf16 v[6:9], v[174:177], v[214:217], v[6:9]
	v_mfma_f32_16x16x32_bf16 v[2:5], v[182:185], v[214:217], v[2:5]
	s_setprio 0
	s_barrier
	s_add_i32 s43, s43, 2
	s_add_u32 s20, s20, 0x100
	s_addc_u32 s21, s21, 0
	s_add_u32 s41, s41, 0x100
	s_addc_u32 s42, s42, 0
	s_cmp_gt_u32 s43, 29
	s_cbranch_scc0 .LBB0_863
	s_and_b64 vcc, exec, s[8:9]
	s_cbranch_vccz .LBB0_866
	s_barrier

.LBB0_941:
	ds_read_b128 v[90:93], v188
	ds_read_b128 v[94:97], v188 offset:1024
	ds_read_b128 v[102:105], v188 offset:2048
	ds_read_b128 v[110:113], v188 offset:3072
	ds_read_b128 v[146:149], v189
	ds_read_b128 v[150:153], v189 offset:1024
	ds_read_b128 v[154:157], v189 offset:2048
	ds_read_b128 v[158:161], v189 offset:3072
	s_add_u32 s30, s28, 0xfff00080
	s_addc_u32 s31, s29, -1
	s_cmp_eq_u32 s51, 60
	s_cselect_b32 s35, s21, s31
	s_cselect_b32 s34, s27, s30
	s_cselect_b32 s31, s19, s50
	s_cselect_b32 s30, s48, s49
	v_lshl_add_u64 v[216:217], s[28:29], 0, v[170:171]
	s_add_i32 m0, s36, 0xc000
	ds_read_b128 v[178:181], v190
	ds_read_b128 v[182:185], v190 offset:1024
	ds_read_b128 v[192:195], v190 offset:2048
	ds_read_b128 v[196:199], v190 offset:3072
	ds_read_b128 v[200:203], v190 offset:4096
	ds_read_b128 v[204:207], v190 offset:5120
	ds_read_b128 v[208:211], v190 offset:6144
	ds_read_b128 v[212:215], v190 offset:7168
	global_load_lds_dwordx4 v[216:217], off
	v_lshl_add_u64 v[216:217], s[28:29], 0, v[172:173]
	s_add_i32 m0, s36, 0xe000
	s_nop 0
	global_load_lds_dwordx4 v[216:217], off
	s_waitcnt vmcnt(8)
	s_waitcnt lgkmcnt(0)
	s_barrier
	s_setprio 1
	s_waitcnt lgkmcnt(0)
	v_mfma_f32_16x16x32_bf16 v[142:145], v[90:93], v[178:181], v[142:145]
	v_mfma_f32_16x16x32_bf16 v[138:141], v[102:105], v[178:181], v[138:141]
	v_mfma_f32_16x16x32_bf16 v[126:129], v[90:93], v[192:195], v[126:129]
	v_mfma_f32_16x16x32_bf16 v[122:125], v[102:105], v[192:195], v[122:125]
	v_mfma_f32_16x16x32_bf16 v[106:109], v[90:93], v[200:203], v[106:109]
	v_mfma_f32_16x16x32_bf16 v[98:101], v[102:105], v[200:203], v[98:101]
	v_mfma_f32_16x16x32_bf16 v[78:81], v[90:93], v[208:211], v[78:81]
	v_mfma_f32_16x16x32_bf16 v[74:77], v[102:105], v[208:211], v[74:77]
	v_mfma_f32_16x16x32_bf16 v[142:145], v[94:97], v[182:185], v[142:145]
	v_mfma_f32_16x16x32_bf16 v[138:141], v[110:113], v[182:185], v[138:141]
	v_mfma_f32_16x16x32_bf16 v[126:129], v[94:97], v[196:199], v[126:129]
	v_mfma_f32_16x16x32_bf16 v[122:125], v[110:113], v[196:199], v[122:125]
	v_mfma_f32_16x16x32_bf16 v[106:109], v[94:97], v[204:207], v[106:109]
	v_mfma_f32_16x16x32_bf16 v[98:101], v[110:113], v[204:207], v[98:101]
	v_mfma_f32_16x16x32_bf16 v[78:81], v[94:97], v[212:215], v[78:81]
	v_mfma_f32_16x16x32_bf16 v[74:77], v[110:113], v[212:215], v[74:77]
	s_setprio 0
	s_setprio 1
	v_mfma_f32_16x16x32_bf16 v[134:137], v[146:149], v[178:181], v[134:137]
	v_mfma_f32_16x16x32_bf16 v[130:133], v[154:157], v[178:181], v[130:133]
	v_mfma_f32_16x16x32_bf16 v[118:121], v[146:149], v[192:195], v[118:121]
	v_mfma_f32_16x16x32_bf16 v[114:117], v[154:157], v[192:195], v[114:117]
	v_mfma_f32_16x16x32_bf16 v[86:89], v[146:149], v[200:203], v[86:89]
	v_mfma_f32_16x16x32_bf16 v[82:85], v[154:157], v[200:203], v[82:85]
	v_mfma_f32_16x16x32_bf16 v[70:73], v[146:149], v[208:211], v[70:73]
	v_mfma_f32_16x16x32_bf16 v[66:69], v[154:157], v[208:211], v[66:69]
	v_mfma_f32_16x16x32_bf16 v[134:137], v[150:153], v[182:185], v[134:137]
	v_mfma_f32_16x16x32_bf16 v[130:133], v[158:161], v[182:185], v[130:133]
	v_mfma_f32_16x16x32_bf16 v[118:121], v[150:153], v[196:199], v[118:121]
	v_mfma_f32_16x16x32_bf16 v[114:117], v[158:161], v[196:199], v[114:117]
	v_mfma_f32_16x16x32_bf16 v[86:89], v[150:153], v[204:207], v[86:89]
	v_mfma_f32_16x16x32_bf16 v[82:85], v[158:161], v[204:207], v[82:85]
	v_mfma_f32_16x16x32_bf16 v[70:73], v[150:153], v[212:215], v[70:73]
	v_mfma_f32_16x16x32_bf16 v[66:69], v[158:161], v[212:215], v[66:69]
	s_setprio 0
	s_barrier
	s_add_i32 s52, s45, s33
	v_lshl_add_u64 v[216:217], s[30:31], 0, v[164:165]
	s_mov_b32 m0, s52
	ds_read_b128 v[178:181], v190 offset:16384
	ds_read_b128 v[182:185], v190 offset:17408
	ds_read_b128 v[192:195], v190 offset:18432
	ds_read_b128 v[196:199], v190 offset:19456
	ds_read_b128 v[200:203], v190 offset:20480
	ds_read_b128 v[204:207], v190 offset:21504
	ds_read_b128 v[208:211], v190 offset:22528
	ds_read_b128 v[212:215], v190 offset:23552
	global_load_lds_dwordx4 v[216:217], off
	s_add_i32 m0, s52, 0x2000
	s_add_u32 s52, s30, 0x100000
	v_lshl_add_u64 v[218:219], s[30:31], 0, v[168:169]
	s_addc_u32 s53, s31, 0
	s_add_i32 s54, s46, s33
	global_load_lds_dwordx4 v[218:219], off
	v_lshl_add_u64 v[220:221], s[52:53], 0, v[164:165]
	s_mov_b32 m0, s54
	v_lshl_add_u64 v[222:223], s[34:35], 0, v[166:167]
	global_load_lds_dwordx4 v[220:221], off
	v_lshl_add_u64 v[220:221], s[52:53], 0, v[168:169]
	s_add_i32 m0, s54, 0x2000
	s_nop 0
	global_load_lds_dwordx4 v[220:221], off
	v_lshl_add_u64 v[220:221], s[34:35], 0, v[162:163]
	s_mov_b32 m0, s36
	s_nop 0
	global_load_lds_dwordx4 v[220:221], off
	s_mov_b32 m0, s37
	s_nop 0
	global_load_lds_dwordx4 v[222:223], off
	s_waitcnt vmcnt(8)
	s_waitcnt lgkmcnt(0)
	s_barrier
	s_setprio 1
	s_waitcnt lgkmcnt(0)
	v_mfma_f32_16x16x32_bf16 v[62:65], v[90:93], v[178:181], v[62:65]
	v_mfma_f32_16x16x32_bf16 v[58:61], v[102:105], v[178:181], v[58:61]
	v_mfma_f32_16x16x32_bf16 v[46:49], v[90:93], v[192:195], v[46:49]
	v_mfma_f32_16x16x32_bf16 v[42:45], v[102:105], v[192:195], v[42:45]
	v_mfma_f32_16x16x32_bf16 v[30:33], v[90:93], v[200:203], v[30:33]
	v_mfma_f32_16x16x32_bf16 v[26:29], v[102:105], v[200:203], v[26:29]
	v_mfma_f32_16x16x32_bf16 v[14:17], v[90:93], v[208:211], v[14:17]
	v_mfma_f32_16x16x32_bf16 v[10:13], v[102:105], v[208:211], v[10:13]
	v_mfma_f32_16x16x32_bf16 v[62:65], v[94:97], v[182:185], v[62:65]
	v_mfma_f32_16x16x32_bf16 v[58:61], v[110:113], v[182:185], v[58:61]
	v_mfma_f32_16x16x32_bf16 v[46:49], v[94:97], v[196:199], v[46:49]
	v_mfma_f32_16x16x32_bf16 v[42:45], v[110:113], v[196:199], v[42:45]
	v_mfma_f32_16x16x32_bf16 v[30:33], v[94:97], v[204:207], v[30:33]
	v_mfma_f32_16x16x32_bf16 v[26:29], v[110:113], v[204:207], v[26:29]
	v_mfma_f32_16x16x32_bf16 v[14:17], v[94:97], v[212:215], v[14:17]
	v_mfma_f32_16x16x32_bf16 v[10:13], v[110:113], v[212:215], v[10:13]
	s_setprio 0
	s_setprio 1
	v_mfma_f32_16x16x32_bf16 v[54:57], v[146:149], v[178:181], v[54:57]
	v_mfma_f32_16x16x32_bf16 v[50:53], v[154:157], v[178:181], v[50:53]
	v_mfma_f32_16x16x32_bf16 v[38:41], v[146:149], v[192:195], v[38:41]
	v_mfma_f32_16x16x32_bf16 v[34:37], v[154:157], v[192:195], v[34:37]
	v_mfma_f32_16x16x32_bf16 v[22:25], v[146:149], v[200:203], v[22:25]
	v_mfma_f32_16x16x32_bf16 v[18:21], v[154:157], v[200:203], v[18:21]
	v_mfma_f32_16x16x32_bf16 v[6:9], v[146:149], v[208:211], v[6:9]
	v_mfma_f32_16x16x32_bf16 v[2:5], v[154:157], v[208:211], v[2:5]
	v_mfma_f32_16x16x32_bf16 v[54:57], v[150:153], v[182:185], v[54:57]
	v_mfma_f32_16x16x32_bf16 v[50:53], v[158:161], v[182:185], v[50:53]
	v_mfma_f32_16x16x32_bf16 v[38:41], v[150:153], v[196:199], v[38:41]
	v_mfma_f32_16x16x32_bf16 v[34:37], v[158:161], v[196:199], v[34:37]
	v_mfma_f32_16x16x32_bf16 v[22:25], v[150:153], v[204:207], v[22:25]
	v_mfma_f32_16x16x32_bf16 v[18:21], v[158:161], v[204:207], v[18:21]
	v_mfma_f32_16x16x32_bf16 v[6:9], v[150:153], v[212:215], v[6:9]
	v_mfma_f32_16x16x32_bf16 v[2:5], v[158:161], v[212:215], v[2:5]
	s_setprio 0
	s_barrier
	s_add_i32 s52, 0, 0x18000
	s_add_i32 s53, 0, 0x1c000
	v_add_u32_e32 v110, s52, v186
	v_add_u32_e32 v158, s53, v186
	ds_read_b128 v[90:93], v110
	ds_read_b128 v[94:97], v110 offset:1024
	ds_read_b128 v[102:105], v110 offset:2048
	ds_read_b128 v[110:113], v110 offset:3072
	ds_read_b128 v[146:149], v158
	ds_read_b128 v[150:153], v158 offset:1024
	ds_read_b128 v[154:157], v158 offset:2048
	ds_read_b128 v[158:161], v158 offset:3072
	s_add_u32 s34, s34, 0x100000
	s_addc_u32 s35, s35, 0
	s_mov_b32 m0, s38
	v_lshl_add_u64 v[224:225], s[34:35], 0, v[162:163]
	ds_read_b128 v[178:181], v190 offset:32768
	ds_read_b128 v[182:185], v190 offset:33792
	ds_read_b128 v[192:195], v190 offset:34816
	ds_read_b128 v[196:199], v190 offset:35840
	ds_read_b128 v[200:203], v190 offset:36864
	ds_read_b128 v[204:207], v190 offset:37888
	ds_read_b128 v[208:211], v190 offset:38912
	ds_read_b128 v[212:215], v190 offset:39936
	global_load_lds_dwordx4 v[224:225], off
	v_lshl_add_u64 v[224:225], s[34:35], 0, v[166:167]
	s_mov_b32 m0, s39
	s_nop 0
	global_load_lds_dwordx4 v[224:225], off
	s_waitcnt vmcnt(8)
	s_waitcnt lgkmcnt(0)
	s_barrier
	s_setprio 1
	s_waitcnt lgkmcnt(0)
	v_mfma_f32_16x16x32_bf16 v[142:145], v[90:93], v[178:181], v[142:145]
	v_mfma_f32_16x16x32_bf16 v[138:141], v[102:105], v[178:181], v[138:141]
	v_mfma_f32_16x16x32_bf16 v[126:129], v[90:93], v[192:195], v[126:129]
	v_mfma_f32_16x16x32_bf16 v[122:125], v[102:105], v[192:195], v[122:125]
	v_mfma_f32_16x16x32_bf16 v[106:109], v[90:93], v[200:203], v[106:109]
	v_mfma_f32_16x16x32_bf16 v[98:101], v[102:105], v[200:203], v[98:101]
	v_mfma_f32_16x16x32_bf16 v[78:81], v[90:93], v[208:211], v[78:81]
	v_mfma_f32_16x16x32_bf16 v[74:77], v[102:105], v[208:211], v[74:77]
	v_mfma_f32_16x16x32_bf16 v[142:145], v[94:97], v[182:185], v[142:145]
	v_mfma_f32_16x16x32_bf16 v[138:141], v[110:113], v[182:185], v[138:141]
	v_mfma_f32_16x16x32_bf16 v[126:129], v[94:97], v[196:199], v[126:129]
	v_mfma_f32_16x16x32_bf16 v[122:125], v[110:113], v[196:199], v[122:125]
	v_mfma_f32_16x16x32_bf16 v[106:109], v[94:97], v[204:207], v[106:109]
	v_mfma_f32_16x16x32_bf16 v[98:101], v[110:113], v[204:207], v[98:101]
	v_mfma_f32_16x16x32_bf16 v[78:81], v[94:97], v[212:215], v[78:81]
	v_mfma_f32_16x16x32_bf16 v[74:77], v[110:113], v[212:215], v[74:77]
	s_setprio 0
	s_setprio 1
	v_mfma_f32_16x16x32_bf16 v[134:137], v[146:149], v[178:181], v[134:137]
	v_mfma_f32_16x16x32_bf16 v[130:133], v[154:157], v[178:181], v[130:133]
	v_mfma_f32_16x16x32_bf16 v[118:121], v[146:149], v[192:195], v[118:121]
	v_mfma_f32_16x16x32_bf16 v[114:117], v[154:157], v[192:195], v[114:117]
	v_mfma_f32_16x16x32_bf16 v[86:89], v[146:149], v[200:203], v[86:89]
	v_mfma_f32_16x16x32_bf16 v[82:85], v[154:157], v[200:203], v[82:85]
	v_mfma_f32_16x16x32_bf16 v[70:73], v[146:149], v[208:211], v[70:73]
	v_mfma_f32_16x16x32_bf16 v[66:69], v[154:157], v[208:211], v[66:69]
	v_mfma_f32_16x16x32_bf16 v[134:137], v[150:153], v[182:185], v[134:137]
	v_mfma_f32_16x16x32_bf16 v[130:133], v[158:161], v[182:185], v[130:133]
	v_mfma_f32_16x16x32_bf16 v[118:121], v[150:153], v[196:199], v[118:121]
	v_mfma_f32_16x16x32_bf16 v[114:117], v[158:161], v[196:199], v[114:117]
	v_mfma_f32_16x16x32_bf16 v[86:89], v[150:153], v[204:207], v[86:89]
	v_mfma_f32_16x16x32_bf16 v[82:85], v[158:161], v[204:207], v[82:85]
	v_mfma_f32_16x16x32_bf16 v[70:73], v[150:153], v[212:215], v[70:73]
	v_mfma_f32_16x16x32_bf16 v[66:69], v[158:161], v[212:215], v[66:69]
	s_setprio 0
	s_barrier
	s_add_i32 s34, s52, s33
	v_lshl_add_u64 v[216:217], v[216:217], 0, s[14:15]
	s_mov_b32 m0, s34
	ds_read_b128 v[178:181], v190 offset:49152
	ds_read_b128 v[182:185], v190 offset:50176
	ds_read_b128 v[192:195], v190 offset:51200
	ds_read_b128 v[196:199], v190 offset:52224
	ds_read_b128 v[200:203], v190 offset:53248
	ds_read_b128 v[204:207], v190 offset:54272
	ds_read_b128 v[208:211], v190 offset:55296
	ds_read_b128 v[212:215], v190 offset:56320
	global_load_lds_dwordx4 v[216:217], off
	s_add_i32 m0, s34, 0x2000
	s_add_u32 s30, s30, 0x100080
	v_lshl_add_u64 v[216:217], v[218:219], 0, s[14:15]
	s_addc_u32 s31, s31, 0
	s_add_i32 s34, s53, s33
	global_load_lds_dwordx4 v[216:217], off
	v_lshl_add_u64 v[216:217], s[30:31], 0, v[164:165]
	s_mov_b32 m0, s34
	s_nop 0
	global_load_lds_dwordx4 v[216:217], off
	v_lshl_add_u64 v[216:217], s[30:31], 0, v[168:169]
	s_add_i32 m0, s34, 0x2000
	s_nop 0
	global_load_lds_dwordx4 v[216:217], off
	v_lshl_add_u64 v[216:217], v[220:221], 0, s[14:15]
	s_mov_b32 m0, s43
	s_nop 0
	global_load_lds_dwordx4 v[216:217], off
	v_lshl_add_u64 v[216:217], v[222:223], 0, s[14:15]
	s_mov_b32 m0, s44
	s_nop 0
	global_load_lds_dwordx4 v[216:217], off
	s_waitcnt vmcnt(8)
	s_waitcnt lgkmcnt(0)
	s_barrier
	s_setprio 1
	s_waitcnt lgkmcnt(0)
	v_mfma_f32_16x16x32_bf16 v[62:65], v[90:93], v[178:181], v[62:65]
	v_mfma_f32_16x16x32_bf16 v[58:61], v[102:105], v[178:181], v[58:61]
	v_mfma_f32_16x16x32_bf16 v[46:49], v[90:93], v[192:195], v[46:49]
	v_mfma_f32_16x16x32_bf16 v[42:45], v[102:105], v[192:195], v[42:45]
	v_mfma_f32_16x16x32_bf16 v[30:33], v[90:93], v[200:203], v[30:33]
	v_mfma_f32_16x16x32_bf16 v[26:29], v[102:105], v[200:203], v[26:29]
	v_mfma_f32_16x16x32_bf16 v[14:17], v[90:93], v[208:211], v[14:17]
	v_mfma_f32_16x16x32_bf16 v[10:13], v[102:105], v[208:211], v[10:13]
	v_mfma_f32_16x16x32_bf16 v[62:65], v[94:97], v[182:185], v[62:65]
	v_mfma_f32_16x16x32_bf16 v[58:61], v[110:113], v[182:185], v[58:61]
	v_mfma_f32_16x16x32_bf16 v[46:49], v[94:97], v[196:199], v[46:49]
	v_mfma_f32_16x16x32_bf16 v[42:45], v[110:113], v[196:199], v[42:45]
	v_mfma_f32_16x16x32_bf16 v[30:33], v[94:97], v[204:207], v[30:33]
	v_mfma_f32_16x16x32_bf16 v[26:29], v[110:113], v[204:207], v[26:29]
	v_mfma_f32_16x16x32_bf16 v[14:17], v[94:97], v[212:215], v[14:17]
	v_mfma_f32_16x16x32_bf16 v[10:13], v[110:113], v[212:215], v[10:13]
	s_setprio 0
	s_setprio 1
	v_mfma_f32_16x16x32_bf16 v[54:57], v[146:149], v[178:181], v[54:57]
	v_mfma_f32_16x16x32_bf16 v[50:53], v[154:157], v[178:181], v[50:53]
	v_mfma_f32_16x16x32_bf16 v[38:41], v[146:149], v[192:195], v[38:41]
	v_mfma_f32_16x16x32_bf16 v[34:37], v[154:157], v[192:195], v[34:37]
	v_mfma_f32_16x16x32_bf16 v[22:25], v[146:149], v[200:203], v[22:25]
	v_mfma_f32_16x16x32_bf16 v[18:21], v[154:157], v[200:203], v[18:21]
	v_mfma_f32_16x16x32_bf16 v[6:9], v[146:149], v[208:211], v[6:9]
	v_mfma_f32_16x16x32_bf16 v[2:5], v[154:157], v[208:211], v[2:5]
	v_mfma_f32_16x16x32_bf16 v[54:57], v[150:153], v[182:185], v[54:57]
	v_mfma_f32_16x16x32_bf16 v[50:53], v[158:161], v[182:185], v[50:53]
	v_mfma_f32_16x16x32_bf16 v[38:41], v[150:153], v[196:199], v[38:41]
	v_mfma_f32_16x16x32_bf16 v[34:37], v[158:161], v[196:199], v[34:37]
	v_mfma_f32_16x16x32_bf16 v[22:25], v[150:153], v[204:207], v[22:25]
	v_mfma_f32_16x16x32_bf16 v[18:21], v[158:161], v[204:207], v[18:21]
	v_mfma_f32_16x16x32_bf16 v[6:9], v[150:153], v[212:215], v[6:9]
	v_mfma_f32_16x16x32_bf16 v[2:5], v[158:161], v[212:215], v[2:5]
	s_setprio 0
	s_barrier
	s_add_i32 s51, s51, 2
	s_add_u32 s28, s28, 0x100
	s_addc_u32 s29, s29, 0
	s_add_u32 s49, s49, 0x100
	s_addc_u32 s50, s50, 0
	s_cmp_gt_u32 s51, 61
	s_cbranch_scc0 .LBB0_941
	s_and_b64 vcc, exec, s[16:17]
	s_cbranch_vccz .LBB0_944
	s_barrier

.LBB0_1080:
.Lprobe_top:
	v_writelane_b32 v246, s0, 0
	v_writelane_b32 v246, s1, 1
	v_writelane_b32 v246, s2, 2
	v_writelane_b32 v246, s3, 3
	v_writelane_b32 v246, s4, 4
	v_writelane_b32 v246, s5, 5
	v_writelane_b32 v246, s6, 6
	v_writelane_b32 v246, s7, 7
	v_writelane_b32 v246, s8, 8
	v_writelane_b32 v246, s9, 9
	v_writelane_b32 v246, s10, 10
	v_writelane_b32 v246, s11, 11
	v_writelane_b32 v246, s12, 12
	v_writelane_b32 v246, s13, 13
	v_writelane_b32 v246, s14, 14
	v_writelane_b32 v246, s15, 15
	v_writelane_b32 v246, s16, 16
	v_writelane_b32 v246, s17, 17
	v_writelane_b32 v246, s18, 18
	v_writelane_b32 v246, s19, 19
	v_writelane_b32 v246, s20, 20
	v_writelane_b32 v246, s21, 21
	v_writelane_b32 v246, s22, 22
	v_writelane_b32 v246, s23, 23
	v_writelane_b32 v246, s24, 24
	v_writelane_b32 v246, s25, 25
	v_writelane_b32 v246, s26, 26
	v_writelane_b32 v246, s27, 27
	v_writelane_b32 v246, s28, 28
	v_writelane_b32 v246, s29, 29
	v_writelane_b32 v246, s30, 30
	v_writelane_b32 v246, s31, 31
	v_writelane_b32 v246, s32, 32
	v_writelane_b32 v246, s33, 33
	v_writelane_b32 v246, s34, 34
	v_writelane_b32 v246, s35, 35
	v_writelane_b32 v246, s36, 36
	v_writelane_b32 v246, s37, 37
	v_writelane_b32 v246, s38, 38
	v_writelane_b32 v246, s39, 39
	v_writelane_b32 v246, s40, 40
	v_writelane_b32 v246, s41, 41
	v_writelane_b32 v246, s42, 42
	v_writelane_b32 v246, s43, 43
	v_writelane_b32 v246, s44, 44
	v_writelane_b32 v246, s45, 45
	v_writelane_b32 v246, s46, 46
	v_writelane_b32 v246, s47, 47
	v_writelane_b32 v246, s48, 48
	v_writelane_b32 v246, s49, 49
	v_writelane_b32 v246, s50, 50
	v_writelane_b32 v246, s51, 51
	v_writelane_b32 v246, s52, 52
	v_writelane_b32 v246, s53, 53
	v_writelane_b32 v246, s54, 54
	v_writelane_b32 v246, s55, 55
	v_writelane_b32 v246, s56, 56
	v_writelane_b32 v246, s57, 57
	v_writelane_b32 v246, s58, 58
	v_writelane_b32 v246, s59, 59
	v_writelane_b32 v246, s60, 60
	v_writelane_b32 v246, s61, 61
	v_writelane_b32 v246, s62, 62
	v_writelane_b32 v246, s63, 63
	v_writelane_b32 v247, s64, 0
	v_writelane_b32 v247, s65, 1
	v_writelane_b32 v247, s66, 2
	v_writelane_b32 v247, s67, 3
	v_writelane_b32 v247, s68, 4
	v_writelane_b32 v247, s69, 5
	v_writelane_b32 v247, s70, 6
	v_writelane_b32 v247, s71, 7
	v_writelane_b32 v247, s72, 8
	v_writelane_b32 v247, s73, 9
	v_writelane_b32 v247, s74, 10
	v_writelane_b32 v247, s75, 11
	v_writelane_b32 v247, s76, 12
	v_writelane_b32 v247, s77, 13
	v_writelane_b32 v247, s78, 14
	v_writelane_b32 v247, s79, 15
	v_writelane_b32 v247, s80, 16
	v_writelane_b32 v247, s81, 17
	v_writelane_b32 v247, s82, 18
	v_writelane_b32 v247, s83, 19
	v_writelane_b32 v247, s84, 20
	v_writelane_b32 v247, s85, 21
	v_writelane_b32 v247, s86, 22
	v_writelane_b32 v247, s87, 23
	v_writelane_b32 v247, s88, 24
	v_writelane_b32 v247, s89, 25
	v_writelane_b32 v247, s90, 26
	v_writelane_b32 v247, s91, 27
	v_writelane_b32 v247, s92, 28
	v_writelane_b32 v247, s93, 29
	v_writelane_b32 v247, s94, 30
	v_writelane_b32 v247, s95, 31
	v_writelane_b32 v247, s96, 32
	v_writelane_b32 v247, s97, 33
	v_writelane_b32 v247, vcc_lo, 34
	v_writelane_b32 v247, vcc_hi, 35
	v_mov_b32_e32 v250, v244
	v_mov_b32_e32 v251, v245
	v_mov_b32_e32 v249, v0
	v_readlane_b32 s100, v248, 0
	s_nop 3
	s_lshl_b32 s100, s100, 8
	s_add_u32 s12, s90, 0x18c00000
	s_addc_u32 s13, s91, 0
	s_add_u32 s14, s90, 0x52800000
	s_addc_u32 s15, s91, 0
	s_add_u32 s16, s90, 0x52e00000
	s_addc_u32 s17, s91, 0
	s_cmp_lt_i32 s58, 10
	s_cselect_b64 s[2:3], -1, 0
	s_cmp_gt_i32 s59, 9
	s_cselect_b64 s[4:5], -1, 0
	s_and_b64 s[2:3], s[2:3], s[4:5]
	s_andn2_b64 vcc, exec, s[2:3]
	s_cbranch_vccnz .LBB0_1241
	v_mov_b32_e32 v1, v0
	s_cmpk_lg_i32 s88, 0x100
	s_cselect_b64 s[94:95], -1, 0
	s_cmpk_eq_i32 s88, 0x100
	v_mov_b32_e32 v1, v0
	s_cselect_b64 s[2:3], -1, 0
	v_writelane_b32 v244, s2, 9
	v_and_b32_e32 v1, 63, v1
	s_and_b64 vcc, exec, s[94:95]
	v_writelane_b32 v244, s3, 10
	s_mov_b64 s[2:3], -1
	s_cbranch_vccnz .LBB0_1087
	s_bitcmp0_b32 s92, 2
	s_cbranch_scc1 .LBB0_1086
	s_lshr_b32 s2, s92, 1
	s_and_b32 s3, s92, 7
	s_and_b32 s2, s2, 0x1ffffffc
	s_add_i32 s3, s3, -4
	s_or_b32 s2, s2, s3
	s_lshl_b32 s2, s2, 3
	s_add_i32 s2, s60, s2
	s_cmpk_gt_i32 s2, 0x2aff
	s_cbranch_scc1 .LBB0_1086
	s_mul_i32 s3, s60, 0x4100
	v_lshlrev_b32_e32 v2, 4, v1
	v_readlane_b32 s20, v245, 0
	s_add_i32 s3, s3, 0
	v_and_b32_e32 v4, 0xf0, v2
	s_waitcnt lgkmcnt(0)
	v_mov_b32_e32 v5, 0
	v_readlane_b32 s22, v245, 2
	v_readlane_b32 s23, v245, 3
	v_add_u32_e32 v9, s3, v4
	v_lshrrev_b32_e32 v8, 3, v1
	v_lshl_add_u64 v[2:3], s[22:23], 0, v[4:5]
	v_lshlrev_b32_e32 v4, 3, v1
	v_and_b32_e32 v4, 56, v4
	v_lshrrev_b32_e32 v6, 4, v1
	v_mul_u32_u24_e32 v7, 0x104, v4
	v_lshlrev_b32_e32 v11, 2, v8
	v_mul_u32_u24_e32 v10, 0x104, v6
	v_add3_u32 v7, s3, v7, v11
	s_mul_i32 s3, s2, 0xac000
	v_lshlrev_b32_e32 v4, 1, v4
	s_movk_i32 s4, 0x2b00
	v_mov_b32_e32 v11, s3
	v_add_u32_e32 v9, v9, v10
	v_lshl_add_u64 v[4:5], s[12:13], 0, v[4:5]
	v_mad_u32_u24 v8, v8, s4, v11
	s_lshl_b32 s3, s2, 6
	v_add_u32_e32 v10, 0x410, v9
	v_add_u32_e32 v11, 0x418, v9
	v_add_u32_e32 v12, 0x820, v9
	v_add_u32_e32 v13, 0x828, v9
	v_add_u32_e32 v14, 0xc30, v9
	v_add_u32_e32 v15, 0xc38, v9
	v_add_u32_e32 v16, 0x1040, v9
	v_add_u32_e32 v17, 0x1048, v9
	v_add_u32_e32 v18, 0x1450, v9
	v_add_u32_e32 v19, 0x1458, v9
	v_add_u32_e32 v20, 0x1860, v9
	v_add_u32_e32 v21, 0x1868, v9
	v_add_u32_e32 v22, 0x1c70, v9
	v_add_u32_e32 v23, 0x1c78, v9
	v_add_u32_e32 v24, 0x2080, v9
	v_add_u32_e32 v25, 0x2088, v9
	v_add_u32_e32 v26, 0x2490, v9
	v_add_u32_e32 v27, 0x2498, v9
	v_add_u32_e32 v28, 0x28a0, v9
	v_add_u32_e32 v29, 0x28a8, v9
	v_add_u32_e32 v30, 0x2cb0, v9
	v_add_u32_e32 v31, 0x2cb8, v9
	v_add_u32_e32 v32, 0x30c0, v9
	v_add_u32_e32 v33, 0x30c8, v9
	v_add_u32_e32 v34, 0x34d0, v9
	v_add_u32_e32 v35, 0x34d8, v9
	v_add_u32_e32 v36, 0x38e0, v9
	v_add_u32_e32 v37, 0x38e8, v9
	v_add_u32_e32 v38, 0x3cf0, v9
	v_add_u32_e32 v39, 0x3cf8, v9
	v_add_u32_e32 v40, 0x400, v7
	v_readlane_b32 s21, v245, 1
	v_readlane_b32 s24, v245, 4
	v_readlane_b32 s25, v245, 5
	v_readlane_b32 s26, v245, 6
	v_readlane_b32 s27, v245, 7

.LBB0_1152:
	s_xor_b64 s[48:49], s[54:55], -1
	s_add_u32 s33, s56, 0x100
	s_addc_u32 s72, s57, 0
	s_ashr_i32 s45, s44, 31
	s_lshl_b64 s[50:51], s[44:45], 21
	s_add_u32 s50, s70, s50
	s_addc_u32 s51, s71, s51
	s_and_b64 s[52:53], s[54:55], exec
	s_cselect_b32 s29, s51, s47
	s_cselect_b32 s45, s50, s46
	s_ashr_i32 s43, s42, 31
	s_lshl_b64 s[52:53], s[42:43], 21
	v_readlane_b32 s20, v244, 4
	v_readlane_b32 s21, v244, 5
	s_add_u32 s52, s20, s52
	s_addc_u32 s53, s21, s53
	s_and_b64 s[58:59], s[54:55], exec
	s_cselect_b32 s43, s53, s57
	s_cselect_b32 s73, s52, s56
	v_lshl_add_u64 v[130:131], s[46:47], 0, v[196:197]
	v_lshl_add_u64 v[132:133], s[46:47], 0, v[198:199]
	s_mov_b32 s83, -2
	s_cmp_eq_u32 s100, 0
	s_cbranch_scc1 .LBB0_1153pre
.LBB0_1153:
	v_add_u32_e32 v146, s78, v187
	v_add_u32_e32 v162, s79, v187
	s_add_u32 s56, s46, s10
	ds_read_b128 v[134:137], v146
	ds_read_b128 v[138:141], v146 offset:1024
	ds_read_b128 v[142:145], v146 offset:2048
	ds_read_b128 v[146:149], v146 offset:3072
	ds_read_b128 v[150:153], v162
	ds_read_b128 v[154:157], v162 offset:1024
	ds_read_b128 v[158:161], v162 offset:2048
	ds_read_b128 v[162:165], v162 offset:3072
	s_addc_u32 s57, s47, s11
	s_add_u32 s56, s56, 0x100
	s_addc_u32 s57, s57, 0
	s_add_u32 s84, s33, s10
	s_addc_u32 s85, s72, s11
	s_cmpk_eq_i32 s10, 0x1f00
	s_cselect_b32 s59, s29, s57
	s_cselect_b32 s58, s45, s56
	s_cselect_b32 s57, s43, s85
	s_cselect_b32 s56, s73, s84
	v_lshl_add_u64 v[222:223], v[130:131], 0, s[10:11]
	s_add_i32 m0, s64, 0xc000
	ds_read_b128 v[166:169], v230
	ds_read_b128 v[170:173], v230 offset:1024
	ds_read_b128 v[174:177], v230 offset:2048
	ds_read_b128 v[202:205], v230 offset:3072
	ds_read_b128 v[206:209], v230 offset:4096
	ds_read_b128 v[210:213], v230 offset:5120
	ds_read_b128 v[214:217], v230 offset:6144
	ds_read_b128 v[218:221], v230 offset:7168
	global_load_lds_dwordx4 v[222:223], off
	v_lshl_add_u64 v[222:223], v[132:133], 0, s[10:11]
	s_add_i32 m0, s64, 0xe000
	s_nop 0
	global_load_lds_dwordx4 v[222:223], off
	s_waitcnt vmcnt(8)
	s_waitcnt lgkmcnt(0)
	s_barrier
	s_setprio 1
	s_waitcnt lgkmcnt(0)
	v_mfma_f32_16x16x32_bf16 v[2:5], v[134:137], v[166:169], v[2:5]
	v_mfma_f32_16x16x32_bf16 v[126:129], v[142:145], v[166:169], v[126:129]
	v_mfma_f32_16x16x32_bf16 v[122:125], v[134:137], v[174:177], v[122:125]
	v_mfma_f32_16x16x32_bf16 v[118:121], v[142:145], v[174:177], v[118:121]
	v_mfma_f32_16x16x32_bf16 v[114:117], v[134:137], v[206:209], v[114:117]
	v_mfma_f32_16x16x32_bf16 v[110:113], v[142:145], v[206:209], v[110:113]
	v_mfma_f32_16x16x32_bf16 v[106:109], v[134:137], v[214:217], v[106:109]
	v_mfma_f32_16x16x32_bf16 v[102:105], v[142:145], v[214:217], v[102:105]
	v_mfma_f32_16x16x32_bf16 v[2:5], v[138:141], v[170:173], v[2:5]
	v_mfma_f32_16x16x32_bf16 v[126:129], v[146:149], v[170:173], v[126:129]
	v_mfma_f32_16x16x32_bf16 v[122:125], v[138:141], v[202:205], v[122:125]
	v_mfma_f32_16x16x32_bf16 v[118:121], v[146:149], v[202:205], v[118:121]
	v_mfma_f32_16x16x32_bf16 v[114:117], v[138:141], v[210:213], v[114:117]
	v_mfma_f32_16x16x32_bf16 v[110:113], v[146:149], v[210:213], v[110:113]
	v_mfma_f32_16x16x32_bf16 v[106:109], v[138:141], v[218:221], v[106:109]
	v_mfma_f32_16x16x32_bf16 v[102:105], v[146:149], v[218:221], v[102:105]
	s_setprio 0
	s_setprio 1
	v_mfma_f32_16x16x32_bf16 v[98:101], v[150:153], v[166:169], v[98:101]
	v_mfma_f32_16x16x32_bf16 v[94:97], v[158:161], v[166:169], v[94:97]
	v_mfma_f32_16x16x32_bf16 v[90:93], v[150:153], v[174:177], v[90:93]
	v_mfma_f32_16x16x32_bf16 v[86:89], v[158:161], v[174:177], v[86:89]
	v_mfma_f32_16x16x32_bf16 v[82:85], v[150:153], v[206:209], v[82:85]
	v_mfma_f32_16x16x32_bf16 v[78:81], v[158:161], v[206:209], v[78:81]
	v_mfma_f32_16x16x32_bf16 v[74:77], v[150:153], v[214:217], v[74:77]
	v_mfma_f32_16x16x32_bf16 v[70:73], v[158:161], v[214:217], v[70:73]
	v_mfma_f32_16x16x32_bf16 v[98:101], v[154:157], v[170:173], v[98:101]
	v_mfma_f32_16x16x32_bf16 v[94:97], v[162:165], v[170:173], v[94:97]
	v_mfma_f32_16x16x32_bf16 v[90:93], v[154:157], v[202:205], v[90:93]
	v_mfma_f32_16x16x32_bf16 v[86:89], v[162:165], v[202:205], v[86:89]
	v_mfma_f32_16x16x32_bf16 v[82:85], v[154:157], v[210:213], v[82:85]
	v_mfma_f32_16x16x32_bf16 v[78:81], v[162:165], v[210:213], v[78:81]
	v_mfma_f32_16x16x32_bf16 v[74:77], v[154:157], v[218:221], v[74:77]
	v_mfma_f32_16x16x32_bf16 v[70:73], v[162:165], v[218:221], v[70:73]
	s_setprio 0
	s_barrier
	s_add_i32 s84, s78, s63
	v_lshl_add_u64 v[222:223], s[56:57], 0, v[180:181]
	s_mov_b32 m0, s84
	ds_read_b128 v[166:169], v230 offset:16384
	ds_read_b128 v[170:173], v230 offset:17408
	ds_read_b128 v[174:177], v230 offset:18432
	ds_read_b128 v[202:205], v230 offset:19456
	ds_read_b128 v[206:209], v230 offset:20480
	ds_read_b128 v[210:213], v230 offset:21504
	ds_read_b128 v[214:217], v230 offset:22528
	ds_read_b128 v[218:221], v230 offset:23552
	global_load_lds_dwordx4 v[222:223], off
	s_add_i32 m0, s84, 0x2000
	s_add_u32 s84, s56, 0x100000
	v_lshl_add_u64 v[232:233], s[56:57], 0, v[184:185]
	s_addc_u32 s85, s57, 0
	s_add_i32 s86, s79, s63
	global_load_lds_dwordx4 v[232:233], off
	v_lshl_add_u64 v[234:235], s[84:85], 0, v[180:181]
	s_mov_b32 m0, s86
	v_lshl_add_u64 v[236:237], s[58:59], 0, v[182:183]
	global_load_lds_dwordx4 v[234:235], off
	v_lshl_add_u64 v[234:235], s[84:85], 0, v[184:185]
	s_add_i32 m0, s86, 0x2000
	s_nop 0
	global_load_lds_dwordx4 v[234:235], off
	v_lshl_add_u64 v[234:235], s[58:59], 0, v[178:179]
	s_mov_b32 m0, s64
	s_nop 0
	global_load_lds_dwordx4 v[234:235], off
	s_mov_b32 m0, s65
	s_nop 0
	global_load_lds_dwordx4 v[236:237], off
	s_waitcnt vmcnt(8)
	s_waitcnt lgkmcnt(0)
	s_barrier
	s_setprio 1
	s_waitcnt lgkmcnt(0)
	v_mfma_f32_16x16x32_bf16 v[66:69], v[134:137], v[166:169], v[66:69]
	v_mfma_f32_16x16x32_bf16 v[62:65], v[142:145], v[166:169], v[62:65]
	v_mfma_f32_16x16x32_bf16 v[58:61], v[134:137], v[174:177], v[58:61]
	v_mfma_f32_16x16x32_bf16 v[54:57], v[142:145], v[174:177], v[54:57]
	v_mfma_f32_16x16x32_bf16 v[50:53], v[134:137], v[206:209], v[50:53]
	v_mfma_f32_16x16x32_bf16 v[46:49], v[142:145], v[206:209], v[46:49]
	v_mfma_f32_16x16x32_bf16 v[42:45], v[134:137], v[214:217], v[42:45]
	v_mfma_f32_16x16x32_bf16 v[38:41], v[142:145], v[214:217], v[38:41]
	v_mfma_f32_16x16x32_bf16 v[66:69], v[138:141], v[170:173], v[66:69]
	v_mfma_f32_16x16x32_bf16 v[62:65], v[146:149], v[170:173], v[62:65]
	v_mfma_f32_16x16x32_bf16 v[58:61], v[138:141], v[202:205], v[58:61]
	v_mfma_f32_16x16x32_bf16 v[54:57], v[146:149], v[202:205], v[54:57]
	v_mfma_f32_16x16x32_bf16 v[50:53], v[138:141], v[210:213], v[50:53]
	v_mfma_f32_16x16x32_bf16 v[46:49], v[146:149], v[210:213], v[46:49]
	v_mfma_f32_16x16x32_bf16 v[42:45], v[138:141], v[218:221], v[42:45]
	v_mfma_f32_16x16x32_bf16 v[38:41], v[146:149], v[218:221], v[38:41]
	s_setprio 0
	s_setprio 1
	v_mfma_f32_16x16x32_bf16 v[34:37], v[150:153], v[166:169], v[34:37]
	v_mfma_f32_16x16x32_bf16 v[30:33], v[158:161], v[166:169], v[30:33]
	v_mfma_f32_16x16x32_bf16 v[26:29], v[150:153], v[174:177], v[26:29]
	v_mfma_f32_16x16x32_bf16 v[22:25], v[158:161], v[174:177], v[22:25]
	v_mfma_f32_16x16x32_bf16 v[18:21], v[150:153], v[206:209], v[18:21]
	v_mfma_f32_16x16x32_bf16 v[14:17], v[158:161], v[206:209], v[14:17]
	v_mfma_f32_16x16x32_bf16 v[10:13], v[150:153], v[214:217], v[10:13]
	v_mfma_f32_16x16x32_bf16 v[6:9], v[158:161], v[214:217], v[6:9]
	v_mfma_f32_16x16x32_bf16 v[34:37], v[154:157], v[170:173], v[34:37]
	v_mfma_f32_16x16x32_bf16 v[30:33], v[162:165], v[170:173], v[30:33]
	v_mfma_f32_16x16x32_bf16 v[26:29], v[154:157], v[202:205], v[26:29]
	v_mfma_f32_16x16x32_bf16 v[22:25], v[162:165], v[202:205], v[22:25]
	v_mfma_f32_16x16x32_bf16 v[18:21], v[154:157], v[210:213], v[18:21]
	v_mfma_f32_16x16x32_bf16 v[14:17], v[162:165], v[210:213], v[14:17]
	v_mfma_f32_16x16x32_bf16 v[10:13], v[154:157], v[218:221], v[10:13]
	v_mfma_f32_16x16x32_bf16 v[6:9], v[162:165], v[218:221], v[6:9]
	s_setprio 0
	s_barrier
	s_add_i32 s84, 0, 0x18000
	s_add_i32 s85, 0, 0x1c000
	v_add_u32_e32 v146, s84, v187
	v_add_u32_e32 v162, s85, v187
	ds_read_b128 v[134:137], v146
	ds_read_b128 v[138:141], v146 offset:1024
	ds_read_b128 v[142:145], v146 offset:2048
	ds_read_b128 v[146:149], v146 offset:3072
	ds_read_b128 v[150:153], v162
	ds_read_b128 v[154:157], v162 offset:1024
	ds_read_b128 v[158:161], v162 offset:2048
	ds_read_b128 v[162:165], v162 offset:3072
	s_add_u32 s58, s58, 0x100000
	s_addc_u32 s59, s59, 0
	s_mov_b32 m0, s67
	v_lshl_add_u64 v[238:239], s[58:59], 0, v[178:179]
	ds_read_b128 v[166:169], v230 offset:32768
	ds_read_b128 v[170:173], v230 offset:33792
	ds_read_b128 v[174:177], v230 offset:34816
	ds_read_b128 v[202:205], v230 offset:35840
	ds_read_b128 v[206:209], v230 offset:36864
	ds_read_b128 v[210:213], v230 offset:37888
	ds_read_b128 v[214:217], v230 offset:38912
	ds_read_b128 v[218:221], v230 offset:39936
	global_load_lds_dwordx4 v[238:239], off
	v_lshl_add_u64 v[238:239], s[58:59], 0, v[182:183]
	s_mov_b32 m0, s68
	s_nop 0
	global_load_lds_dwordx4 v[238:239], off
	s_waitcnt vmcnt(8)
	s_waitcnt lgkmcnt(0)
	s_barrier
	s_setprio 1
	s_waitcnt lgkmcnt(0)
	v_mfma_f32_16x16x32_bf16 v[2:5], v[134:137], v[166:169], v[2:5]
	v_mfma_f32_16x16x32_bf16 v[126:129], v[142:145], v[166:169], v[126:129]
	v_mfma_f32_16x16x32_bf16 v[122:125], v[134:137], v[174:177], v[122:125]
	v_mfma_f32_16x16x32_bf16 v[118:121], v[142:145], v[174:177], v[118:121]
	v_mfma_f32_16x16x32_bf16 v[114:117], v[134:137], v[206:209], v[114:117]
	v_mfma_f32_16x16x32_bf16 v[110:113], v[142:145], v[206:209], v[110:113]
	v_mfma_f32_16x16x32_bf16 v[106:109], v[134:137], v[214:217], v[106:109]
	v_mfma_f32_16x16x32_bf16 v[102:105], v[142:145], v[214:217], v[102:105]
	v_mfma_f32_16x16x32_bf16 v[2:5], v[138:141], v[170:173], v[2:5]
	v_mfma_f32_16x16x32_bf16 v[126:129], v[146:149], v[170:173], v[126:129]
	v_mfma_f32_16x16x32_bf16 v[122:125], v[138:141], v[202:205], v[122:125]
	v_mfma_f32_16x16x32_bf16 v[118:121], v[146:149], v[202:205], v[118:121]
	v_mfma_f32_16x16x32_bf16 v[114:117], v[138:141], v[210:213], v[114:117]
	v_mfma_f32_16x16x32_bf16 v[110:113], v[146:149], v[210:213], v[110:113]
	v_mfma_f32_16x16x32_bf16 v[106:109], v[138:141], v[218:221], v[106:109]
	v_mfma_f32_16x16x32_bf16 v[102:105], v[146:149], v[218:221], v[102:105]
	s_setprio 0
	s_setprio 1
	v_mfma_f32_16x16x32_bf16 v[98:101], v[150:153], v[166:169], v[98:101]
	v_mfma_f32_16x16x32_bf16 v[94:97], v[158:161], v[166:169], v[94:97]
	v_mfma_f32_16x16x32_bf16 v[90:93], v[150:153], v[174:177], v[90:93]
	v_mfma_f32_16x16x32_bf16 v[86:89], v[158:161], v[174:177], v[86:89]
	v_mfma_f32_16x16x32_bf16 v[82:85], v[150:153], v[206:209], v[82:85]
	v_mfma_f32_16x16x32_bf16 v[78:81], v[158:161], v[206:209], v[78:81]
	v_mfma_f32_16x16x32_bf16 v[74:77], v[150:153], v[214:217], v[74:77]
	v_mfma_f32_16x16x32_bf16 v[70:73], v[158:161], v[214:217], v[70:73]
	v_mfma_f32_16x16x32_bf16 v[98:101], v[154:157], v[170:173], v[98:101]
	v_mfma_f32_16x16x32_bf16 v[94:97], v[162:165], v[170:173], v[94:97]
	v_mfma_f32_16x16x32_bf16 v[90:93], v[154:157], v[202:205], v[90:93]
	v_mfma_f32_16x16x32_bf16 v[86:89], v[162:165], v[202:205], v[86:89]
	v_mfma_f32_16x16x32_bf16 v[82:85], v[154:157], v[210:213], v[82:85]
	v_mfma_f32_16x16x32_bf16 v[78:81], v[162:165], v[210:213], v[78:81]
	v_mfma_f32_16x16x32_bf16 v[74:77], v[154:157], v[218:221], v[74:77]
	v_mfma_f32_16x16x32_bf16 v[70:73], v[162:165], v[218:221], v[70:73]
	s_setprio 0
	s_barrier
	s_add_i32 s58, s84, s63
	v_lshl_add_u64 v[222:223], v[222:223], 0, s[34:35]
	s_mov_b32 m0, s58
	ds_read_b128 v[166:169], v230 offset:49152
	ds_read_b128 v[170:173], v230 offset:50176
	ds_read_b128 v[174:177], v230 offset:51200
	ds_read_b128 v[202:205], v230 offset:52224
	ds_read_b128 v[206:209], v230 offset:53248
	ds_read_b128 v[210:213], v230 offset:54272
	ds_read_b128 v[214:217], v230 offset:55296
	ds_read_b128 v[218:221], v230 offset:56320
	global_load_lds_dwordx4 v[222:223], off
	s_add_i32 m0, s58, 0x2000
	s_add_u32 s56, s56, 0x100080
	v_lshl_add_u64 v[222:223], v[232:233], 0, s[34:35]
	s_addc_u32 s57, s57, 0
	s_add_i32 s58, s85, s63
	global_load_lds_dwordx4 v[222:223], off
	v_lshl_add_u64 v[222:223], s[56:57], 0, v[180:181]
	s_mov_b32 m0, s58
	s_nop 0
	global_load_lds_dwordx4 v[222:223], off
	v_lshl_add_u64 v[222:223], s[56:57], 0, v[184:185]
	s_add_i32 m0, s58, 0x2000
	s_nop 0
	global_load_lds_dwordx4 v[222:223], off
	v_lshl_add_u64 v[222:223], v[234:235], 0, s[34:35]
	s_mov_b32 m0, s74
	s_nop 0
	global_load_lds_dwordx4 v[222:223], off
	v_lshl_add_u64 v[222:223], v[236:237], 0, s[34:35]
	s_mov_b32 m0, s75
	s_nop 0
	global_load_lds_dwordx4 v[222:223], off
	s_waitcnt vmcnt(8)
	s_waitcnt lgkmcnt(0)
	s_barrier
	s_setprio 1
	s_waitcnt lgkmcnt(0)
	v_mfma_f32_16x16x32_bf16 v[66:69], v[134:137], v[166:169], v[66:69]
	v_mfma_f32_16x16x32_bf16 v[62:65], v[142:145], v[166:169], v[62:65]
	v_mfma_f32_16x16x32_bf16 v[58:61], v[134:137], v[174:177], v[58:61]
	v_mfma_f32_16x16x32_bf16 v[54:57], v[142:145], v[174:177], v[54:57]
	v_mfma_f32_16x16x32_bf16 v[50:53], v[134:137], v[206:209], v[50:53]
	v_mfma_f32_16x16x32_bf16 v[46:49], v[142:145], v[206:209], v[46:49]
	v_mfma_f32_16x16x32_bf16 v[42:45], v[134:137], v[214:217], v[42:45]
	v_mfma_f32_16x16x32_bf16 v[38:41], v[142:145], v[214:217], v[38:41]
	v_mfma_f32_16x16x32_bf16 v[66:69], v[138:141], v[170:173], v[66:69]
	v_mfma_f32_16x16x32_bf16 v[62:65], v[146:149], v[170:173], v[62:65]
	v_mfma_f32_16x16x32_bf16 v[58:61], v[138:141], v[202:205], v[58:61]
	v_mfma_f32_16x16x32_bf16 v[54:57], v[146:149], v[202:205], v[54:57]
	v_mfma_f32_16x16x32_bf16 v[50:53], v[138:141], v[210:213], v[50:53]
	v_mfma_f32_16x16x32_bf16 v[46:49], v[146:149], v[210:213], v[46:49]
	v_mfma_f32_16x16x32_bf16 v[42:45], v[138:141], v[218:221], v[42:45]
	v_mfma_f32_16x16x32_bf16 v[38:41], v[146:149], v[218:221], v[38:41]
	s_setprio 0
	s_setprio 1
	v_mfma_f32_16x16x32_bf16 v[34:37], v[150:153], v[166:169], v[34:37]
	v_mfma_f32_16x16x32_bf16 v[30:33], v[158:161], v[166:169], v[30:33]
	v_mfma_f32_16x16x32_bf16 v[26:29], v[150:153], v[174:177], v[26:29]
	v_mfma_f32_16x16x32_bf16 v[22:25], v[158:161], v[174:177], v[22:25]
	v_mfma_f32_16x16x32_bf16 v[18:21], v[150:153], v[206:209], v[18:21]
	v_mfma_f32_16x16x32_bf16 v[14:17], v[158:161], v[206:209], v[14:17]
	v_mfma_f32_16x16x32_bf16 v[10:13], v[150:153], v[214:217], v[10:13]
	v_mfma_f32_16x16x32_bf16 v[6:9], v[158:161], v[214:217], v[6:9]
	v_mfma_f32_16x16x32_bf16 v[34:37], v[154:157], v[170:173], v[34:37]
	v_mfma_f32_16x16x32_bf16 v[30:33], v[162:165], v[170:173], v[30:33]
	v_mfma_f32_16x16x32_bf16 v[26:29], v[154:157], v[202:205], v[26:29]
	v_mfma_f32_16x16x32_bf16 v[22:25], v[162:165], v[202:205], v[22:25]
	v_mfma_f32_16x16x32_bf16 v[18:21], v[154:157], v[210:213], v[18:21]
	v_mfma_f32_16x16x32_bf16 v[14:17], v[162:165], v[210:213], v[14:17]
	v_mfma_f32_16x16x32_bf16 v[10:13], v[154:157], v[218:221], v[10:13]
	v_mfma_f32_16x16x32_bf16 v[6:9], v[162:165], v[218:221], v[6:9]
	s_setprio 0
	s_barrier
	s_add_i32 s83, s83, 2
	s_add_u32 s10, s10, s100
	s_addc_u32 s11, s11, 0
	s_cmp_gt_u32 s83, 61
	s_cbranch_scc0 .LBB0_1153
.Lexit1153:
	s_and_b64 vcc, exec, s[36:37]
	s_cbranch_vccz .LBB0_1156
	s_barrier

.LBB0_1241:
	v_readlane_b32 s98, v248, 0
	s_nop 3
	s_cmp_lg_u32 s98, 0
	s_cbranch_scc1 .Lprobe_cont
	v_writelane_b32 v248, 1, 0
	v_readlane_b32 s0, v246, 0
	v_readlane_b32 s1, v246, 1
	v_readlane_b32 s2, v246, 2
	v_readlane_b32 s3, v246, 3
	v_readlane_b32 s4, v246, 4
	v_readlane_b32 s5, v246, 5
	v_readlane_b32 s6, v246, 6
	v_readlane_b32 s7, v246, 7
	v_readlane_b32 s8, v246, 8
	v_readlane_b32 s9, v246, 9
	v_readlane_b32 s10, v246, 10
	v_readlane_b32 s11, v246, 11
	v_readlane_b32 s12, v246, 12
	v_readlane_b32 s13, v246, 13
	v_readlane_b32 s14, v246, 14
	v_readlane_b32 s15, v246, 15
	v_readlane_b32 s16, v246, 16
	v_readlane_b32 s17, v246, 17
	v_readlane_b32 s18, v246, 18
	v_readlane_b32 s19, v246, 19
	v_readlane_b32 s20, v246, 20
	v_readlane_b32 s21, v246, 21
	v_readlane_b32 s22, v246, 22
	v_readlane_b32 s23, v246, 23
	v_readlane_b32 s24, v246, 24
	v_readlane_b32 s25, v246, 25
	v_readlane_b32 s26, v246, 26
	v_readlane_b32 s27, v246, 27
	v_readlane_b32 s28, v246, 28
	v_readlane_b32 s29, v246, 29
	v_readlane_b32 s30, v246, 30
	v_readlane_b32 s31, v246, 31
	v_readlane_b32 s32, v246, 32
	v_readlane_b32 s33, v246, 33
	v_readlane_b32 s34, v246, 34
	v_readlane_b32 s35, v246, 35
	v_readlane_b32 s36, v246, 36
	v_readlane_b32 s37, v246, 37
	v_readlane_b32 s38, v246, 38
	v_readlane_b32 s39, v246, 39
	v_readlane_b32 s40, v246, 40
	v_readlane_b32 s41, v246, 41
	v_readlane_b32 s42, v246, 42
	v_readlane_b32 s43, v246, 43
	v_readlane_b32 s44, v246, 44
	v_readlane_b32 s45, v246, 45
	v_readlane_b32 s46, v246, 46
	v_readlane_b32 s47, v246, 47
	v_readlane_b32 s48, v246, 48
	v_readlane_b32 s49, v246, 49
	v_readlane_b32 s50, v246, 50
	v_readlane_b32 s51, v246, 51
	v_readlane_b32 s52, v246, 52
	v_readlane_b32 s53, v246, 53
	v_readlane_b32 s54, v246, 54
	v_readlane_b32 s55, v246, 55
	v_readlane_b32 s56, v246, 56
	v_readlane_b32 s57, v246, 57
	v_readlane_b32 s58, v246, 58
	v_readlane_b32 s59, v246, 59
	v_readlane_b32 s60, v246, 60
	v_readlane_b32 s61, v246, 61
	v_readlane_b32 s62, v246, 62
	v_readlane_b32 s63, v246, 63
	v_readlane_b32 s64, v247, 0
	v_readlane_b32 s65, v247, 1
	v_readlane_b32 s66, v247, 2
	v_readlane_b32 s67, v247, 3
	v_readlane_b32 s68, v247, 4
	v_readlane_b32 s69, v247, 5
	v_readlane_b32 s70, v247, 6
	v_readlane_b32 s71, v247, 7
	v_readlane_b32 s72, v247, 8
	v_readlane_b32 s73, v247, 9
	v_readlane_b32 s74, v247, 10
	v_readlane_b32 s75, v247, 11
	v_readlane_b32 s76, v247, 12
	v_readlane_b32 s77, v247, 13
	v_readlane_b32 s78, v247, 14
	v_readlane_b32 s79, v247, 15
	v_readlane_b32 s80, v247, 16
	v_readlane_b32 s81, v247, 17
	v_readlane_b32 s82, v247, 18
	v_readlane_b32 s83, v247, 19
	v_readlane_b32 s84, v247, 20
	v_readlane_b32 s85, v247, 21
	v_readlane_b32 s86, v247, 22
	v_readlane_b32 s87, v247, 23
	v_readlane_b32 s88, v247, 24
	v_readlane_b32 s89, v247, 25
	v_readlane_b32 s90, v247, 26
	v_readlane_b32 s91, v247, 27
	v_readlane_b32 s92, v247, 28
	v_readlane_b32 s93, v247, 29
	v_readlane_b32 s94, v247, 30
	v_readlane_b32 s95, v247, 31
	v_readlane_b32 s96, v247, 32
	v_readlane_b32 s97, v247, 33
	v_readlane_b32 vcc_lo, v247, 34
	v_readlane_b32 vcc_hi, v247, 35
	v_mov_b32_e32 v244, v250
	v_mov_b32_e32 v245, v251
	v_mov_b32_e32 v0, v249
	s_nop 7
	s_branch .Lprobe_top

.LBB0_1325:
	ds_read_b128 v[130:133], v176
	ds_read_b128 v[134:137], v176 offset:1024
	ds_read_b128 v[138:141], v176 offset:2048
	ds_read_b128 v[142:145], v176 offset:3072
	ds_read_b128 v[146:149], v177
	ds_read_b128 v[166:169], v177 offset:1024
	ds_read_b128 v[170:173], v177 offset:2048
	ds_read_b128 v[180:183], v177 offset:3072
	s_add_u32 s26, s24, 0xffd50080
	s_addc_u32 s27, s25, -1
	s_cmpk_eq_i32 s49, 0xa8
	s_cselect_b32 s29, s5, s27
	s_cselect_b32 s28, s4, s26
	s_cselect_b32 s27, s23, s48
	s_cselect_b32 s26, s22, s47
	v_lshl_add_u64 v[216:217], s[24:25], 0, v[158:159]
	s_add_i32 m0, s33, 0xc000
	ds_read_b128 v[184:187], v178
	ds_read_b128 v[188:191], v178 offset:1024
	ds_read_b128 v[192:195], v178 offset:2048
	ds_read_b128 v[196:199], v178 offset:3072
	ds_read_b128 v[200:203], v178 offset:4096
	ds_read_b128 v[204:207], v178 offset:5120
	ds_read_b128 v[208:211], v178 offset:6144
	ds_read_b128 v[212:215], v178 offset:7168
	global_load_lds_dwordx4 v[216:217], off
	v_lshl_add_u64 v[216:217], s[24:25], 0, v[160:161]
	s_add_i32 m0, s33, 0xe000
	s_nop 0
	global_load_lds_dwordx4 v[216:217], off
	s_waitcnt vmcnt(8)
	s_waitcnt lgkmcnt(0)
	s_barrier
	s_setprio 1
	s_waitcnt lgkmcnt(0)
	v_mfma_f32_16x16x32_bf16 v[126:129], v[130:133], v[184:187], v[126:129]
	v_mfma_f32_16x16x32_bf16 v[122:125], v[138:141], v[184:187], v[122:125]
	v_mfma_f32_16x16x32_bf16 v[110:113], v[130:133], v[192:195], v[110:113]
	v_mfma_f32_16x16x32_bf16 v[106:109], v[138:141], v[192:195], v[106:109]
	v_mfma_f32_16x16x32_bf16 v[94:97], v[130:133], v[200:203], v[94:97]
	v_mfma_f32_16x16x32_bf16 v[90:93], v[138:141], v[200:203], v[90:93]
	v_mfma_f32_16x16x32_bf16 v[78:81], v[130:133], v[208:211], v[78:81]
	v_mfma_f32_16x16x32_bf16 v[74:77], v[138:141], v[208:211], v[74:77]
	v_mfma_f32_16x16x32_bf16 v[126:129], v[134:137], v[188:191], v[126:129]
	v_mfma_f32_16x16x32_bf16 v[122:125], v[142:145], v[188:191], v[122:125]
	v_mfma_f32_16x16x32_bf16 v[110:113], v[134:137], v[196:199], v[110:113]
	v_mfma_f32_16x16x32_bf16 v[106:109], v[142:145], v[196:199], v[106:109]
	v_mfma_f32_16x16x32_bf16 v[94:97], v[134:137], v[204:207], v[94:97]
	v_mfma_f32_16x16x32_bf16 v[90:93], v[142:145], v[204:207], v[90:93]
	v_mfma_f32_16x16x32_bf16 v[78:81], v[134:137], v[212:215], v[78:81]
	v_mfma_f32_16x16x32_bf16 v[74:77], v[142:145], v[212:215], v[74:77]
	s_setprio 0
	s_setprio 1
	v_mfma_f32_16x16x32_bf16 v[118:121], v[146:149], v[184:187], v[118:121]
	v_mfma_f32_16x16x32_bf16 v[114:117], v[170:173], v[184:187], v[114:117]
	v_mfma_f32_16x16x32_bf16 v[102:105], v[146:149], v[192:195], v[102:105]
	v_mfma_f32_16x16x32_bf16 v[98:101], v[170:173], v[192:195], v[98:101]
	v_mfma_f32_16x16x32_bf16 v[86:89], v[146:149], v[200:203], v[86:89]
	v_mfma_f32_16x16x32_bf16 v[82:85], v[170:173], v[200:203], v[82:85]
	v_mfma_f32_16x16x32_bf16 v[70:73], v[146:149], v[208:211], v[70:73]
	v_mfma_f32_16x16x32_bf16 v[66:69], v[170:173], v[208:211], v[66:69]
	v_mfma_f32_16x16x32_bf16 v[118:121], v[166:169], v[188:191], v[118:121]
	v_mfma_f32_16x16x32_bf16 v[114:117], v[180:183], v[188:191], v[114:117]
	v_mfma_f32_16x16x32_bf16 v[102:105], v[166:169], v[196:199], v[102:105]
	v_mfma_f32_16x16x32_bf16 v[98:101], v[180:183], v[196:199], v[98:101]
	v_mfma_f32_16x16x32_bf16 v[86:89], v[166:169], v[204:207], v[86:89]
	v_mfma_f32_16x16x32_bf16 v[82:85], v[180:183], v[204:207], v[82:85]
	v_mfma_f32_16x16x32_bf16 v[70:73], v[166:169], v[212:215], v[70:73]
	v_mfma_f32_16x16x32_bf16 v[66:69], v[180:183], v[212:215], v[66:69]
	s_setprio 0
	s_barrier
	s_add_i32 s50, s41, s31
	v_lshl_add_u64 v[216:217], s[26:27], 0, v[152:153]
	s_mov_b32 m0, s50
	ds_read_b128 v[184:187], v178 offset:16384
	ds_read_b128 v[188:191], v178 offset:17408
	ds_read_b128 v[192:195], v178 offset:18432
	ds_read_b128 v[196:199], v178 offset:19456
	ds_read_b128 v[200:203], v178 offset:20480
	ds_read_b128 v[204:207], v178 offset:21504
	ds_read_b128 v[208:211], v178 offset:22528
	ds_read_b128 v[212:215], v178 offset:23552
	global_load_lds_dwordx4 v[216:217], off
	s_add_i32 m0, s50, 0x2000
	s_add_u32 s50, s26, 0x2b0000
	v_lshl_add_u64 v[218:219], s[26:27], 0, v[156:157]
	s_addc_u32 s51, s27, 0
	s_add_i32 s52, s42, s31
	global_load_lds_dwordx4 v[218:219], off
	v_lshl_add_u64 v[220:221], s[50:51], 0, v[152:153]
	s_mov_b32 m0, s52
	v_lshl_add_u64 v[222:223], s[28:29], 0, v[154:155]
	global_load_lds_dwordx4 v[220:221], off
	v_lshl_add_u64 v[220:221], s[50:51], 0, v[156:157]
	s_add_i32 m0, s52, 0x2000
	s_nop 0
	global_load_lds_dwordx4 v[220:221], off
	v_lshl_add_u64 v[220:221], s[28:29], 0, v[150:151]
	s_mov_b32 m0, s33
	s_nop 0
	global_load_lds_dwordx4 v[220:221], off
	s_mov_b32 m0, s34
	s_nop 0
	global_load_lds_dwordx4 v[222:223], off
	s_waitcnt vmcnt(8)
	s_waitcnt lgkmcnt(0)
	s_barrier
	s_setprio 1
	s_waitcnt lgkmcnt(0)
	v_mfma_f32_16x16x32_bf16 v[62:65], v[130:133], v[184:187], v[62:65]
	v_mfma_f32_16x16x32_bf16 v[58:61], v[138:141], v[184:187], v[58:61]
	v_mfma_f32_16x16x32_bf16 v[46:49], v[130:133], v[192:195], v[46:49]
	v_mfma_f32_16x16x32_bf16 v[42:45], v[138:141], v[192:195], v[42:45]
	v_mfma_f32_16x16x32_bf16 v[30:33], v[130:133], v[200:203], v[30:33]
	v_mfma_f32_16x16x32_bf16 v[26:29], v[138:141], v[200:203], v[26:29]
	v_mfma_f32_16x16x32_bf16 v[14:17], v[130:133], v[208:211], v[14:17]
	v_mfma_f32_16x16x32_bf16 v[10:13], v[138:141], v[208:211], v[10:13]
	v_mfma_f32_16x16x32_bf16 v[62:65], v[134:137], v[188:191], v[62:65]
	v_mfma_f32_16x16x32_bf16 v[58:61], v[142:145], v[188:191], v[58:61]
	v_mfma_f32_16x16x32_bf16 v[46:49], v[134:137], v[196:199], v[46:49]
	v_mfma_f32_16x16x32_bf16 v[42:45], v[142:145], v[196:199], v[42:45]
	v_mfma_f32_16x16x32_bf16 v[30:33], v[134:137], v[204:207], v[30:33]
	v_mfma_f32_16x16x32_bf16 v[26:29], v[142:145], v[204:207], v[26:29]
	v_mfma_f32_16x16x32_bf16 v[14:17], v[134:137], v[212:215], v[14:17]
	v_mfma_f32_16x16x32_bf16 v[10:13], v[142:145], v[212:215], v[10:13]
	s_setprio 0
	s_setprio 1
	v_mfma_f32_16x16x32_bf16 v[54:57], v[146:149], v[184:187], v[54:57]
	v_mfma_f32_16x16x32_bf16 v[50:53], v[170:173], v[184:187], v[50:53]
	v_mfma_f32_16x16x32_bf16 v[38:41], v[146:149], v[192:195], v[38:41]
	v_mfma_f32_16x16x32_bf16 v[34:37], v[170:173], v[192:195], v[34:37]
	v_mfma_f32_16x16x32_bf16 v[22:25], v[146:149], v[200:203], v[22:25]
	v_mfma_f32_16x16x32_bf16 v[18:21], v[170:173], v[200:203], v[18:21]
	v_mfma_f32_16x16x32_bf16 v[6:9], v[146:149], v[208:211], v[6:9]
	v_mfma_f32_16x16x32_bf16 v[2:5], v[170:173], v[208:211], v[2:5]
	v_mfma_f32_16x16x32_bf16 v[54:57], v[166:169], v[188:191], v[54:57]
	v_mfma_f32_16x16x32_bf16 v[50:53], v[180:183], v[188:191], v[50:53]
	v_mfma_f32_16x16x32_bf16 v[38:41], v[166:169], v[196:199], v[38:41]
	v_mfma_f32_16x16x32_bf16 v[34:37], v[180:183], v[196:199], v[34:37]
	v_mfma_f32_16x16x32_bf16 v[22:25], v[166:169], v[204:207], v[22:25]
	v_mfma_f32_16x16x32_bf16 v[18:21], v[180:183], v[204:207], v[18:21]
	v_mfma_f32_16x16x32_bf16 v[6:9], v[166:169], v[212:215], v[6:9]
	v_mfma_f32_16x16x32_bf16 v[2:5], v[180:183], v[212:215], v[2:5]
	s_setprio 0
	s_barrier
	s_add_i32 s50, 0, 0x18000
	s_add_i32 s51, 0, 0x1c000
	v_add_u32_e32 v142, s50, v174
	v_add_u32_e32 v179, s51, v174
	ds_read_b128 v[130:133], v142
	ds_read_b128 v[134:137], v142 offset:1024
	ds_read_b128 v[138:141], v142 offset:2048
	ds_read_b128 v[142:145], v142 offset:3072
	ds_read_b128 v[146:149], v179
	ds_read_b128 v[166:169], v179 offset:1024
	ds_read_b128 v[170:173], v179 offset:2048
	ds_read_b128 v[180:183], v179 offset:3072
	s_add_u32 s28, s28, 0x2b0000
	s_addc_u32 s29, s29, 0
	s_mov_b32 m0, s35
	v_lshl_add_u64 v[224:225], s[28:29], 0, v[150:151]
	ds_read_b128 v[184:187], v178 offset:32768
	ds_read_b128 v[188:191], v178 offset:33792
	ds_read_b128 v[192:195], v178 offset:34816
	ds_read_b128 v[196:199], v178 offset:35840
	ds_read_b128 v[200:203], v178 offset:36864
	ds_read_b128 v[204:207], v178 offset:37888
	ds_read_b128 v[208:211], v178 offset:38912
	ds_read_b128 v[212:215], v178 offset:39936
	global_load_lds_dwordx4 v[224:225], off
	v_lshl_add_u64 v[224:225], s[28:29], 0, v[154:155]
	s_mov_b32 m0, s36
	s_nop 0
	global_load_lds_dwordx4 v[224:225], off
	s_waitcnt vmcnt(8)
	s_waitcnt lgkmcnt(0)
	s_barrier
	s_setprio 1
	s_waitcnt lgkmcnt(0)
	v_mfma_f32_16x16x32_bf16 v[126:129], v[130:133], v[184:187], v[126:129]
	v_mfma_f32_16x16x32_bf16 v[122:125], v[138:141], v[184:187], v[122:125]
	v_mfma_f32_16x16x32_bf16 v[110:113], v[130:133], v[192:195], v[110:113]
	v_mfma_f32_16x16x32_bf16 v[106:109], v[138:141], v[192:195], v[106:109]
	v_mfma_f32_16x16x32_bf16 v[94:97], v[130:133], v[200:203], v[94:97]
	v_mfma_f32_16x16x32_bf16 v[90:93], v[138:141], v[200:203], v[90:93]
	v_mfma_f32_16x16x32_bf16 v[78:81], v[130:133], v[208:211], v[78:81]
	v_mfma_f32_16x16x32_bf16 v[74:77], v[138:141], v[208:211], v[74:77]
	v_mfma_f32_16x16x32_bf16 v[126:129], v[134:137], v[188:191], v[126:129]
	v_mfma_f32_16x16x32_bf16 v[122:125], v[142:145], v[188:191], v[122:125]
	v_mfma_f32_16x16x32_bf16 v[110:113], v[134:137], v[196:199], v[110:113]
	v_mfma_f32_16x16x32_bf16 v[106:109], v[142:145], v[196:199], v[106:109]
	v_mfma_f32_16x16x32_bf16 v[94:97], v[134:137], v[204:207], v[94:97]
	v_mfma_f32_16x16x32_bf16 v[90:93], v[142:145], v[204:207], v[90:93]
	v_mfma_f32_16x16x32_bf16 v[78:81], v[134:137], v[212:215], v[78:81]
	v_mfma_f32_16x16x32_bf16 v[74:77], v[142:145], v[212:215], v[74:77]
	s_setprio 0
	s_setprio 1
	v_mfma_f32_16x16x32_bf16 v[118:121], v[146:149], v[184:187], v[118:121]
	v_mfma_f32_16x16x32_bf16 v[114:117], v[170:173], v[184:187], v[114:117]
	v_mfma_f32_16x16x32_bf16 v[102:105], v[146:149], v[192:195], v[102:105]
	v_mfma_f32_16x16x32_bf16 v[98:101], v[170:173], v[192:195], v[98:101]
	v_mfma_f32_16x16x32_bf16 v[86:89], v[146:149], v[200:203], v[86:89]
	v_mfma_f32_16x16x32_bf16 v[82:85], v[170:173], v[200:203], v[82:85]
	v_mfma_f32_16x16x32_bf16 v[70:73], v[146:149], v[208:211], v[70:73]
	v_mfma_f32_16x16x32_bf16 v[66:69], v[170:173], v[208:211], v[66:69]
	v_mfma_f32_16x16x32_bf16 v[118:121], v[166:169], v[188:191], v[118:121]
	v_mfma_f32_16x16x32_bf16 v[114:117], v[180:183], v[188:191], v[114:117]
	v_mfma_f32_16x16x32_bf16 v[102:105], v[166:169], v[196:199], v[102:105]
	v_mfma_f32_16x16x32_bf16 v[98:101], v[180:183], v[196:199], v[98:101]
	v_mfma_f32_16x16x32_bf16 v[86:89], v[166:169], v[204:207], v[86:89]
	v_mfma_f32_16x16x32_bf16 v[82:85], v[180:183], v[204:207], v[82:85]
	v_mfma_f32_16x16x32_bf16 v[70:73], v[166:169], v[212:215], v[70:73]
	v_mfma_f32_16x16x32_bf16 v[66:69], v[180:183], v[212:215], v[66:69]
	s_setprio 0
	s_barrier
	s_add_i32 s28, s50, s31
	v_lshl_add_u64 v[216:217], v[216:217], 0, s[8:9]
	s_mov_b32 m0, s28
	ds_read_b128 v[184:187], v178 offset:49152
	ds_read_b128 v[188:191], v178 offset:50176
	ds_read_b128 v[192:195], v178 offset:51200
	ds_read_b128 v[196:199], v178 offset:52224
	ds_read_b128 v[200:203], v178 offset:53248
	ds_read_b128 v[204:207], v178 offset:54272
	ds_read_b128 v[208:211], v178 offset:55296
	ds_read_b128 v[212:215], v178 offset:56320
	global_load_lds_dwordx4 v[216:217], off
	s_add_i32 m0, s28, 0x2000
	s_add_u32 s26, s26, 0x2b0080
	v_lshl_add_u64 v[216:217], v[218:219], 0, s[8:9]
	s_addc_u32 s27, s27, 0
	s_add_i32 s28, s51, s31
	global_load_lds_dwordx4 v[216:217], off
	v_lshl_add_u64 v[216:217], s[26:27], 0, v[152:153]
	s_mov_b32 m0, s28
	s_nop 0
	global_load_lds_dwordx4 v[216:217], off
	v_lshl_add_u64 v[216:217], s[26:27], 0, v[156:157]
	s_add_i32 m0, s28, 0x2000
	s_nop 0
	global_load_lds_dwordx4 v[216:217], off
	v_lshl_add_u64 v[216:217], v[220:221], 0, s[8:9]
	s_mov_b32 m0, s38
	s_nop 0
	global_load_lds_dwordx4 v[216:217], off
	v_lshl_add_u64 v[216:217], v[222:223], 0, s[8:9]
	s_mov_b32 m0, s39
	s_nop 0
	global_load_lds_dwordx4 v[216:217], off
	s_waitcnt vmcnt(8)
	s_waitcnt lgkmcnt(0)
	s_barrier
	s_setprio 1
	s_waitcnt lgkmcnt(0)
	v_mfma_f32_16x16x32_bf16 v[62:65], v[130:133], v[184:187], v[62:65]
	v_mfma_f32_16x16x32_bf16 v[58:61], v[138:141], v[184:187], v[58:61]
	v_mfma_f32_16x16x32_bf16 v[46:49], v[130:133], v[192:195], v[46:49]
	v_mfma_f32_16x16x32_bf16 v[42:45], v[138:141], v[192:195], v[42:45]
	v_mfma_f32_16x16x32_bf16 v[30:33], v[130:133], v[200:203], v[30:33]
	v_mfma_f32_16x16x32_bf16 v[26:29], v[138:141], v[200:203], v[26:29]
	v_mfma_f32_16x16x32_bf16 v[14:17], v[130:133], v[208:211], v[14:17]
	v_mfma_f32_16x16x32_bf16 v[10:13], v[138:141], v[208:211], v[10:13]
	v_mfma_f32_16x16x32_bf16 v[62:65], v[134:137], v[188:191], v[62:65]
	v_mfma_f32_16x16x32_bf16 v[58:61], v[142:145], v[188:191], v[58:61]
	v_mfma_f32_16x16x32_bf16 v[46:49], v[134:137], v[196:199], v[46:49]
	v_mfma_f32_16x16x32_bf16 v[42:45], v[142:145], v[196:199], v[42:45]
	v_mfma_f32_16x16x32_bf16 v[30:33], v[134:137], v[204:207], v[30:33]
	v_mfma_f32_16x16x32_bf16 v[26:29], v[142:145], v[204:207], v[26:29]
	v_mfma_f32_16x16x32_bf16 v[14:17], v[134:137], v[212:215], v[14:17]
	v_mfma_f32_16x16x32_bf16 v[10:13], v[142:145], v[212:215], v[10:13]
	s_setprio 0
	s_setprio 1
	v_mfma_f32_16x16x32_bf16 v[54:57], v[146:149], v[184:187], v[54:57]
	v_mfma_f32_16x16x32_bf16 v[50:53], v[170:173], v[184:187], v[50:53]
	v_mfma_f32_16x16x32_bf16 v[38:41], v[146:149], v[192:195], v[38:41]
	v_mfma_f32_16x16x32_bf16 v[34:37], v[170:173], v[192:195], v[34:37]
	v_mfma_f32_16x16x32_bf16 v[22:25], v[146:149], v[200:203], v[22:25]
	v_mfma_f32_16x16x32_bf16 v[18:21], v[170:173], v[200:203], v[18:21]
	v_mfma_f32_16x16x32_bf16 v[6:9], v[146:149], v[208:211], v[6:9]
	v_mfma_f32_16x16x32_bf16 v[2:5], v[170:173], v[208:211], v[2:5]
	v_mfma_f32_16x16x32_bf16 v[54:57], v[166:169], v[188:191], v[54:57]
	v_mfma_f32_16x16x32_bf16 v[50:53], v[180:183], v[188:191], v[50:53]
	v_mfma_f32_16x16x32_bf16 v[38:41], v[166:169], v[196:199], v[38:41]
	v_mfma_f32_16x16x32_bf16 v[34:37], v[180:183], v[196:199], v[34:37]
	v_mfma_f32_16x16x32_bf16 v[22:25], v[166:169], v[204:207], v[22:25]
	v_mfma_f32_16x16x32_bf16 v[18:21], v[180:183], v[204:207], v[18:21]
	v_mfma_f32_16x16x32_bf16 v[6:9], v[166:169], v[212:215], v[6:9]
	v_mfma_f32_16x16x32_bf16 v[2:5], v[180:183], v[212:215], v[2:5]
	s_setprio 0
	s_barrier
	s_add_i32 s49, s49, 2
	s_add_u32 s24, s24, 0x100
	s_addc_u32 s25, s25, 0
	s_add_u32 s47, s47, 0x100
	s_addc_u32 s48, s48, 0
	s_cmpk_gt_u32 s49, 0xa9
	s_cbranch_scc0 .LBB0_1325
	s_and_b64 vcc, exec, s[10:11]
	s_cbranch_vccz .LBB0_1328
	s_barrier

.LBB0_1153pre:
	s_branch .Lexit1153
	v_readfirstlane_b32 s101, v0
	s_nop 3
	s_lshr_b32 s101, s101, 8
	s_cmp_eq_u32 s101, 0
	s_cselect_b64 vcc, -1, 0
.LBB0_1153x:
	v_add_u32_e32 v146, s78, v187
	v_add_u32_e32 v162, s79, v187
	s_add_u32 s56, s46, s10
	ds_read_b128 v[134:137], v146
	ds_read_b128 v[138:141], v146 offset:1024
	ds_read_b128 v[142:145], v146 offset:2048
	ds_read_b128 v[146:149], v146 offset:3072
	ds_read_b128 v[150:153], v162
	ds_read_b128 v[154:157], v162 offset:1024
	ds_read_b128 v[158:161], v162 offset:2048
	ds_read_b128 v[162:165], v162 offset:3072
	s_addc_u32 s57, s47, s11
	s_add_u32 s56, s56, 0x100
	s_addc_u32 s57, s57, 0
	s_add_u32 s84, s33, s10
	s_addc_u32 s85, s72, s11
	s_cmpk_eq_i32 s10, 0x1f00
	s_cselect_b32 s59, s29, s57
	s_cselect_b32 s58, s45, s56
	s_cselect_b32 s57, s43, s85
	s_cselect_b32 s56, s73, s84
	v_lshl_add_u64 v[222:223], v[130:131], 0, s[10:11]
	s_add_i32 m0, s64, 0xc000
	ds_read_b128 v[166:169], v230
	ds_read_b128 v[170:173], v230 offset:1024
	ds_read_b128 v[174:177], v230 offset:2048
	ds_read_b128 v[202:205], v230 offset:3072
	ds_read_b128 v[206:209], v230 offset:4096
	ds_read_b128 v[210:213], v230 offset:5120
	ds_read_b128 v[214:217], v230 offset:6144
	ds_read_b128 v[218:221], v230 offset:7168
	global_load_lds_dwordx4 v[222:223], off
	v_lshl_add_u64 v[222:223], v[132:133], 0, s[10:11]
	s_add_i32 m0, s64, 0xe000
	s_nop 0
	global_load_lds_dwordx4 v[222:223], off
	s_waitcnt vmcnt(8)
	s_waitcnt lgkmcnt(0)
	s_barrier
	s_setprio 1
	s_waitcnt lgkmcnt(0)
	v_mfma_f32_16x16x32_bf16 v[2:5], v[134:137], v[166:169], v[2:5]
	v_mfma_f32_16x16x32_bf16 v[126:129], v[142:145], v[166:169], v[126:129]
	v_mfma_f32_16x16x32_bf16 v[122:125], v[134:137], v[174:177], v[122:125]
	v_mfma_f32_16x16x32_bf16 v[118:121], v[142:145], v[174:177], v[118:121]
	v_mfma_f32_16x16x32_bf16 v[114:117], v[134:137], v[206:209], v[114:117]
	v_mfma_f32_16x16x32_bf16 v[110:113], v[142:145], v[206:209], v[110:113]
	v_mfma_f32_16x16x32_bf16 v[106:109], v[134:137], v[214:217], v[106:109]
	v_mfma_f32_16x16x32_bf16 v[102:105], v[142:145], v[214:217], v[102:105]
	v_mfma_f32_16x16x32_bf16 v[2:5], v[138:141], v[170:173], v[2:5]
	v_mfma_f32_16x16x32_bf16 v[126:129], v[146:149], v[170:173], v[126:129]
	v_mfma_f32_16x16x32_bf16 v[122:125], v[138:141], v[202:205], v[122:125]
	v_mfma_f32_16x16x32_bf16 v[118:121], v[146:149], v[202:205], v[118:121]
	v_mfma_f32_16x16x32_bf16 v[114:117], v[138:141], v[210:213], v[114:117]
	v_mfma_f32_16x16x32_bf16 v[110:113], v[146:149], v[210:213], v[110:113]
	v_mfma_f32_16x16x32_bf16 v[106:109], v[138:141], v[218:221], v[106:109]
	v_mfma_f32_16x16x32_bf16 v[102:105], v[146:149], v[218:221], v[102:105]
	s_setprio 0
	s_setprio 1
	v_mfma_f32_16x16x32_bf16 v[98:101], v[150:153], v[166:169], v[98:101]
	v_mfma_f32_16x16x32_bf16 v[94:97], v[158:161], v[166:169], v[94:97]
	v_mfma_f32_16x16x32_bf16 v[90:93], v[150:153], v[174:177], v[90:93]
	v_mfma_f32_16x16x32_bf16 v[86:89], v[158:161], v[174:177], v[86:89]
	v_mfma_f32_16x16x32_bf16 v[82:85], v[150:153], v[206:209], v[82:85]
	v_mfma_f32_16x16x32_bf16 v[78:81], v[158:161], v[206:209], v[78:81]
	v_mfma_f32_16x16x32_bf16 v[74:77], v[150:153], v[214:217], v[74:77]
	v_mfma_f32_16x16x32_bf16 v[70:73], v[158:161], v[214:217], v[70:73]
	v_mfma_f32_16x16x32_bf16 v[98:101], v[154:157], v[170:173], v[98:101]
	v_mfma_f32_16x16x32_bf16 v[94:97], v[162:165], v[170:173], v[94:97]
	v_mfma_f32_16x16x32_bf16 v[90:93], v[154:157], v[202:205], v[90:93]
	v_mfma_f32_16x16x32_bf16 v[86:89], v[162:165], v[202:205], v[86:89]
	v_mfma_f32_16x16x32_bf16 v[82:85], v[154:157], v[210:213], v[82:85]
	v_mfma_f32_16x16x32_bf16 v[78:81], v[162:165], v[210:213], v[78:81]
	v_mfma_f32_16x16x32_bf16 v[74:77], v[154:157], v[218:221], v[74:77]
	v_mfma_f32_16x16x32_bf16 v[70:73], v[162:165], v[218:221], v[70:73]
	s_setprio 0
	s_barrier
	s_add_i32 s84, s78, s63
	v_lshl_add_u64 v[222:223], s[56:57], 0, v[180:181]
	s_mov_b32 m0, s84
	ds_read_b128 v[166:169], v230 offset:16384
	ds_read_b128 v[170:173], v230 offset:17408
	ds_read_b128 v[174:177], v230 offset:18432
	ds_read_b128 v[202:205], v230 offset:19456
	ds_read_b128 v[206:209], v230 offset:20480
	ds_read_b128 v[210:213], v230 offset:21504
	ds_read_b128 v[214:217], v230 offset:22528
	ds_read_b128 v[218:221], v230 offset:23552
	global_load_lds_dwordx4 v[222:223], off
	s_add_i32 m0, s84, 0x2000
	s_add_u32 s84, s56, 0x100000
	v_lshl_add_u64 v[232:233], s[56:57], 0, v[184:185]
	s_addc_u32 s85, s57, 0
	s_add_i32 s86, s79, s63
	global_load_lds_dwordx4 v[232:233], off
	v_lshl_add_u64 v[234:235], s[84:85], 0, v[180:181]
	s_mov_b32 m0, s86
	v_lshl_add_u64 v[236:237], s[58:59], 0, v[182:183]
	global_load_lds_dwordx4 v[234:235], off
	v_lshl_add_u64 v[234:235], s[84:85], 0, v[184:185]
	s_add_i32 m0, s86, 0x2000
	s_nop 0
	global_load_lds_dwordx4 v[234:235], off
	v_lshl_add_u64 v[234:235], s[58:59], 0, v[178:179]
	s_mov_b32 m0, s64
	s_nop 0
	global_load_lds_dwordx4 v[234:235], off
	s_mov_b32 m0, s65
	s_nop 0
	global_load_lds_dwordx4 v[236:237], off
	s_waitcnt vmcnt(8)
	s_waitcnt lgkmcnt(0)
	s_barrier
	s_setprio 1
	s_waitcnt lgkmcnt(0)
	v_mfma_f32_16x16x32_bf16 v[66:69], v[134:137], v[166:169], v[66:69]
	v_mfma_f32_16x16x32_bf16 v[62:65], v[142:145], v[166:169], v[62:65]
	v_mfma_f32_16x16x32_bf16 v[58:61], v[134:137], v[174:177], v[58:61]
	v_mfma_f32_16x16x32_bf16 v[54:57], v[142:145], v[174:177], v[54:57]
	v_mfma_f32_16x16x32_bf16 v[50:53], v[134:137], v[206:209], v[50:53]
	v_mfma_f32_16x16x32_bf16 v[46:49], v[142:145], v[206:209], v[46:49]
	v_mfma_f32_16x16x32_bf16 v[42:45], v[134:137], v[214:217], v[42:45]
	v_mfma_f32_16x16x32_bf16 v[38:41], v[142:145], v[214:217], v[38:41]
	v_mfma_f32_16x16x32_bf16 v[66:69], v[138:141], v[170:173], v[66:69]
	v_mfma_f32_16x16x32_bf16 v[62:65], v[146:149], v[170:173], v[62:65]
	v_mfma_f32_16x16x32_bf16 v[58:61], v[138:141], v[202:205], v[58:61]
	v_mfma_f32_16x16x32_bf16 v[54:57], v[146:149], v[202:205], v[54:57]
	v_mfma_f32_16x16x32_bf16 v[50:53], v[138:141], v[210:213], v[50:53]
	v_mfma_f32_16x16x32_bf16 v[46:49], v[146:149], v[210:213], v[46:49]
	v_mfma_f32_16x16x32_bf16 v[42:45], v[138:141], v[218:221], v[42:45]
	v_mfma_f32_16x16x32_bf16 v[38:41], v[146:149], v[218:221], v[38:41]
	s_setprio 0
	s_setprio 1
	v_mfma_f32_16x16x32_bf16 v[34:37], v[150:153], v[166:169], v[34:37]
	v_mfma_f32_16x16x32_bf16 v[30:33], v[158:161], v[166:169], v[30:33]
	v_mfma_f32_16x16x32_bf16 v[26:29], v[150:153], v[174:177], v[26:29]
	v_mfma_f32_16x16x32_bf16 v[22:25], v[158:161], v[174:177], v[22:25]
	v_mfma_f32_16x16x32_bf16 v[18:21], v[150:153], v[206:209], v[18:21]
	v_mfma_f32_16x16x32_bf16 v[14:17], v[158:161], v[206:209], v[14:17]
	v_mfma_f32_16x16x32_bf16 v[10:13], v[150:153], v[214:217], v[10:13]
	v_mfma_f32_16x16x32_bf16 v[6:9], v[158:161], v[214:217], v[6:9]
	v_mfma_f32_16x16x32_bf16 v[34:37], v[154:157], v[170:173], v[34:37]
	v_mfma_f32_16x16x32_bf16 v[30:33], v[162:165], v[170:173], v[30:33]
	v_mfma_f32_16x16x32_bf16 v[26:29], v[154:157], v[202:205], v[26:29]
	v_mfma_f32_16x16x32_bf16 v[22:25], v[162:165], v[202:205], v[22:25]
	v_mfma_f32_16x16x32_bf16 v[18:21], v[154:157], v[210:213], v[18:21]
	v_mfma_f32_16x16x32_bf16 v[14:17], v[162:165], v[210:213], v[14:17]
	v_mfma_f32_16x16x32_bf16 v[10:13], v[154:157], v[218:221], v[10:13]
	v_mfma_f32_16x16x32_bf16 v[6:9], v[162:165], v[218:221], v[6:9]
	s_setprio 0
	s_barrier
	s_add_i32 s84, 0, 0x18000
	s_add_i32 s85, 0, 0x1c000
	v_add_u32_e32 v146, s84, v187
	v_add_u32_e32 v162, s85, v187
	ds_read_b128 v[134:137], v146
	ds_read_b128 v[138:141], v146 offset:1024
	ds_read_b128 v[142:145], v146 offset:2048
	ds_read_b128 v[146:149], v146 offset:3072
	ds_read_b128 v[150:153], v162
	ds_read_b128 v[154:157], v162 offset:1024
	ds_read_b128 v[158:161], v162 offset:2048
	ds_read_b128 v[162:165], v162 offset:3072
	s_add_u32 s58, s58, 0x100000
	s_addc_u32 s59, s59, 0
	s_mov_b32 m0, s67
	v_lshl_add_u64 v[238:239], s[58:59], 0, v[178:179]
	ds_read_b128 v[166:169], v230 offset:32768
	ds_read_b128 v[170:173], v230 offset:33792
	ds_read_b128 v[174:177], v230 offset:34816
	ds_read_b128 v[202:205], v230 offset:35840
	ds_read_b128 v[206:209], v230 offset:36864
	ds_read_b128 v[210:213], v230 offset:37888
	ds_read_b128 v[214:217], v230 offset:38912
	ds_read_b128 v[218:221], v230 offset:39936
	global_load_lds_dwordx4 v[238:239], off
	v_lshl_add_u64 v[238:239], s[58:59], 0, v[182:183]
	s_mov_b32 m0, s68
	s_nop 0
	global_load_lds_dwordx4 v[238:239], off
	s_waitcnt vmcnt(8)
	s_waitcnt lgkmcnt(0)
	s_barrier
	s_setprio 1
	s_waitcnt lgkmcnt(0)
	v_mfma_f32_16x16x32_bf16 v[2:5], v[134:137], v[166:169], v[2:5]
	v_mfma_f32_16x16x32_bf16 v[126:129], v[142:145], v[166:169], v[126:129]
	v_mfma_f32_16x16x32_bf16 v[122:125], v[134:137], v[174:177], v[122:125]
	v_mfma_f32_16x16x32_bf16 v[118:121], v[142:145], v[174:177], v[118:121]
	v_mfma_f32_16x16x32_bf16 v[114:117], v[134:137], v[206:209], v[114:117]
	v_mfma_f32_16x16x32_bf16 v[110:113], v[142:145], v[206:209], v[110:113]
	v_mfma_f32_16x16x32_bf16 v[106:109], v[134:137], v[214:217], v[106:109]
	v_mfma_f32_16x16x32_bf16 v[102:105], v[142:145], v[214:217], v[102:105]
	v_mfma_f32_16x16x32_bf16 v[2:5], v[138:141], v[170:173], v[2:5]
	v_mfma_f32_16x16x32_bf16 v[126:129], v[146:149], v[170:173], v[126:129]
	v_mfma_f32_16x16x32_bf16 v[122:125], v[138:141], v[202:205], v[122:125]
	v_mfma_f32_16x16x32_bf16 v[118:121], v[146:149], v[202:205], v[118:121]
	v_mfma_f32_16x16x32_bf16 v[114:117], v[138:141], v[210:213], v[114:117]
	v_mfma_f32_16x16x32_bf16 v[110:113], v[146:149], v[210:213], v[110:113]
	v_mfma_f32_16x16x32_bf16 v[106:109], v[138:141], v[218:221], v[106:109]
	v_mfma_f32_16x16x32_bf16 v[102:105], v[146:149], v[218:221], v[102:105]
	s_setprio 0
	s_setprio 1
	v_mfma_f32_16x16x32_bf16 v[98:101], v[150:153], v[166:169], v[98:101]
	v_mfma_f32_16x16x32_bf16 v[94:97], v[158:161], v[166:169], v[94:97]
	v_mfma_f32_16x16x32_bf16 v[90:93], v[150:153], v[174:177], v[90:93]
	v_mfma_f32_16x16x32_bf16 v[86:89], v[158:161], v[174:177], v[86:89]
	v_mfma_f32_16x16x32_bf16 v[82:85], v[150:153], v[206:209], v[82:85]
	v_mfma_f32_16x16x32_bf16 v[78:81], v[158:161], v[206:209], v[78:81]
	v_mfma_f32_16x16x32_bf16 v[74:77], v[150:153], v[214:217], v[74:77]
	v_mfma_f32_16x16x32_bf16 v[70:73], v[158:161], v[214:217], v[70:73]
	v_mfma_f32_16x16x32_bf16 v[98:101], v[154:157], v[170:173], v[98:101]
	v_mfma_f32_16x16x32_bf16 v[94:97], v[162:165], v[170:173], v[94:97]
	v_mfma_f32_16x16x32_bf16 v[90:93], v[154:157], v[202:205], v[90:93]
	v_mfma_f32_16x16x32_bf16 v[86:89], v[162:165], v[202:205], v[86:89]
	v_mfma_f32_16x16x32_bf16 v[82:85], v[154:157], v[210:213], v[82:85]
	v_mfma_f32_16x16x32_bf16 v[78:81], v[162:165], v[210:213], v[78:81]
	v_mfma_f32_16x16x32_bf16 v[74:77], v[154:157], v[218:221], v[74:77]
	v_mfma_f32_16x16x32_bf16 v[70:73], v[162:165], v[218:221], v[70:73]
	s_setprio 0
	s_barrier
	s_add_i32 s58, s84, s63
	v_lshl_add_u64 v[222:223], v[222:223], 0, s[34:35]
	s_mov_b32 m0, s58
	ds_read_b128 v[166:169], v230 offset:49152
	ds_read_b128 v[170:173], v230 offset:50176
	ds_read_b128 v[174:177], v230 offset:51200
	ds_read_b128 v[202:205], v230 offset:52224
	ds_read_b128 v[206:209], v230 offset:53248
	ds_read_b128 v[210:213], v230 offset:54272
	ds_read_b128 v[214:217], v230 offset:55296
	ds_read_b128 v[218:221], v230 offset:56320
	global_load_lds_dwordx4 v[222:223], off
	s_add_i32 m0, s58, 0x2000
	s_add_u32 s56, s56, 0x100080
	v_lshl_add_u64 v[222:223], v[232:233], 0, s[34:35]
	s_addc_u32 s57, s57, 0
	s_add_i32 s58, s85, s63
	global_load_lds_dwordx4 v[222:223], off
	v_lshl_add_u64 v[222:223], s[56:57], 0, v[180:181]
	s_mov_b32 m0, s58
	s_nop 0
	global_load_lds_dwordx4 v[222:223], off
	v_lshl_add_u64 v[222:223], s[56:57], 0, v[184:185]
	s_add_i32 m0, s58, 0x2000
	s_nop 0
	global_load_lds_dwordx4 v[222:223], off
	v_lshl_add_u64 v[222:223], v[234:235], 0, s[34:35]
	s_mov_b32 m0, s74
	s_nop 0
	global_load_lds_dwordx4 v[222:223], off
	v_lshl_add_u64 v[222:223], v[236:237], 0, s[34:35]
	s_mov_b32 m0, s75
	s_nop 0
	global_load_lds_dwordx4 v[222:223], off
	s_waitcnt vmcnt(8)
	s_waitcnt lgkmcnt(0)
	s_barrier
	s_setprio 1
	s_waitcnt lgkmcnt(0)
	v_mfma_f32_16x16x32_bf16 v[66:69], v[134:137], v[166:169], v[66:69]
	v_mfma_f32_16x16x32_bf16 v[62:65], v[142:145], v[166:169], v[62:65]
	v_mfma_f32_16x16x32_bf16 v[58:61], v[134:137], v[174:177], v[58:61]
	v_mfma_f32_16x16x32_bf16 v[54:57], v[142:145], v[174:177], v[54:57]
	v_mfma_f32_16x16x32_bf16 v[50:53], v[134:137], v[206:209], v[50:53]
	v_mfma_f32_16x16x32_bf16 v[46:49], v[142:145], v[206:209], v[46:49]
	v_mfma_f32_16x16x32_bf16 v[42:45], v[134:137], v[214:217], v[42:45]
	v_mfma_f32_16x16x32_bf16 v[38:41], v[142:145], v[214:217], v[38:41]
	v_mfma_f32_16x16x32_bf16 v[66:69], v[138:141], v[170:173], v[66:69]
	v_mfma_f32_16x16x32_bf16 v[62:65], v[146:149], v[170:173], v[62:65]
	v_mfma_f32_16x16x32_bf16 v[58:61], v[138:141], v[202:205], v[58:61]
	v_mfma_f32_16x16x32_bf16 v[54:57], v[146:149], v[202:205], v[54:57]
	v_mfma_f32_16x16x32_bf16 v[50:53], v[138:141], v[210:213], v[50:53]
	v_mfma_f32_16x16x32_bf16 v[46:49], v[146:149], v[210:213], v[46:49]
	v_mfma_f32_16x16x32_bf16 v[42:45], v[138:141], v[218:221], v[42:45]
	v_mfma_f32_16x16x32_bf16 v[38:41], v[146:149], v[218:221], v[38:41]
	s_setprio 0
	s_setprio 1
	v_mfma_f32_16x16x32_bf16 v[34:37], v[150:153], v[166:169], v[34:37]
	v_mfma_f32_16x16x32_bf16 v[30:33], v[158:161], v[166:169], v[30:33]
	v_mfma_f32_16x16x32_bf16 v[26:29], v[150:153], v[174:177], v[26:29]
	v_mfma_f32_16x16x32_bf16 v[22:25], v[158:161], v[174:177], v[22:25]
	v_mfma_f32_16x16x32_bf16 v[18:21], v[150:153], v[206:209], v[18:21]
	v_mfma_f32_16x16x32_bf16 v[14:17], v[158:161], v[206:209], v[14:17]
	v_mfma_f32_16x16x32_bf16 v[10:13], v[150:153], v[214:217], v[10:13]
	v_mfma_f32_16x16x32_bf16 v[6:9], v[158:161], v[214:217], v[6:9]
	v_mfma_f32_16x16x32_bf16 v[34:37], v[154:157], v[170:173], v[34:37]
	v_mfma_f32_16x16x32_bf16 v[30:33], v[162:165], v[170:173], v[30:33]
	v_mfma_f32_16x16x32_bf16 v[26:29], v[154:157], v[202:205], v[26:29]
	v_mfma_f32_16x16x32_bf16 v[22:25], v[162:165], v[202:205], v[22:25]
	v_mfma_f32_16x16x32_bf16 v[18:21], v[154:157], v[210:213], v[18:21]
	v_mfma_f32_16x16x32_bf16 v[14:17], v[162:165], v[210:213], v[14:17]
	v_mfma_f32_16x16x32_bf16 v[10:13], v[154:157], v[218:221], v[10:13]
	v_mfma_f32_16x16x32_bf16 v[6:9], v[162:165], v[218:221], v[6:9]
	s_setprio 0
	s_barrier
	s_add_i32 s83, s83, 2
	s_add_u32 s10, s10, s100
	s_addc_u32 s11, s11, 0
	s_cmp_gt_u32 s83, 61
	s_cbranch_scc0 .LBB0_1153x
	s_branch .Lexit1153

	.amdhsa_kernel _Z6mk_fwd4Args
		.amdhsa_group_segment_fixed_size 0
		.amdhsa_private_segment_fixed_size 0
		.amdhsa_kernarg_size 496
		.amdhsa_user_sgpr_count 2
		.amdhsa_user_sgpr_dispatch_ptr 0
		.amdhsa_user_sgpr_queue_ptr 0
		.amdhsa_user_sgpr_kernarg_segment_ptr 1
		.amdhsa_user_sgpr_dispatch_id 0
		.amdhsa_user_sgpr_kernarg_preload_length 0
		.amdhsa_user_sgpr_kernarg_preload_offset 0
		.amdhsa_user_sgpr_private_segment_size 0
		.amdhsa_uses_dynamic_stack 0
		.amdhsa_enable_private_segment 0
		.amdhsa_system_sgpr_workgroup_id_x 1
		.amdhsa_system_sgpr_workgroup_id_y 0
		.amdhsa_system_sgpr_workgroup_id_z 0
		.amdhsa_system_sgpr_workgroup_info 0
		.amdhsa_system_vgpr_workitem_id 0
		.amdhsa_next_free_vgpr 253
		.amdhsa_next_free_sgpr 102
		.amdhsa_accum_offset 256
		.amdhsa_reserve_vcc 1
		.amdhsa_float_round_mode_32 0
		.amdhsa_float_round_mode_16_64 0
		.amdhsa_float_denorm_mode_32 3
		.amdhsa_float_denorm_mode_16_64 3
		.amdhsa_dx10_clamp 1
		.amdhsa_ieee_mode 1
		.amdhsa_fp16_overflow 0
		.amdhsa_tg_split 0
		.amdhsa_exception_fp_ieee_invalid_op 0
		.amdhsa_exception_fp_denorm_src 0
		.amdhsa_exception_fp_ieee_div_zero 0
		.amdhsa_exception_fp_ieee_overflow 0
		.amdhsa_exception_fp_ieee_underflow 0
		.amdhsa_exception_fp_ieee_inexact 0
		.amdhsa_exception_int_div_zero 0
	.end_amdhsa_kernel

amdhsa.kernels:
  - .agpr_count:     0
    .args:
      - .offset:         0
        .size:           240
        .value_kind:     by_value
      - .offset:         240
        .size:           4
        .value_kind:     hidden_block_count_x
      - .offset:         244
        .size:           4
        .value_kind:     hidden_block_count_y
      - .offset:         248
        .size:           4
        .value_kind:     hidden_block_count_z
      - .offset:         252
        .size:           2
        .value_kind:     hidden_group_size_x
      - .offset:         254
        .size:           2
        .value_kind:     hidden_group_size_y
      - .offset:         256
        .size:           2
        .value_kind:     hidden_group_size_z
      - .offset:         258
        .size:           2
        .value_kind:     hidden_remainder_x
      - .offset:         260
        .size:           2
        .value_kind:     hidden_remainder_y
      - .offset:         262
        .size:           2
        .value_kind:     hidden_remainder_z
      - .offset:         280
        .size:           8
        .value_kind:     hidden_global_offset_x
      - .offset:         288
        .size:           8
        .value_kind:     hidden_global_offset_y
      - .offset:         296
        .size:           8
        .value_kind:     hidden_global_offset_z
      - .offset:         304
        .size:           2
        .value_kind:     hidden_grid_dims
      - .offset:         360
        .size:           4
        .value_kind:     hidden_dynamic_lds_size
    .group_segment_fixed_size: 0
    .kernarg_segment_align: 8
    .kernarg_segment_size: 496
    .language:       OpenCL C
    .language_version:
      - 2
      - 0
    .max_flat_workgroup_size: 512
    .name:           _Z6mk_fwd4Args
    .private_segment_fixed_size: 0
    .sgpr_count:     108
    .sgpr_spill_count: 138
    .symbol:         _Z6mk_fwd4Args.kd
    .uniform_work_group_size: 1
    .uses_dynamic_stack: false
    .vgpr_count:     253
    .vgpr_spill_count: 0
    .wavefront_size: 64
